# transpose loops: next-tile loads stay in flight through store phase; phase5 staging loads batched; both pooling branches rewritten
# speedup vs baseline: 1.0320x; 1.0173x over previous
; __device__ __forceinline__ void transpose_jobs(const TJob* jobs, int njobs, int bi, int nblk, LAS unsigned char* lds) {
;     ...
;     f32x4 v[4]; int curj = 0, base = 0;
;     int t = bi;
;     auto locate = [&](int tt, int& jj, int& bb) { while (tt >= bb + (jobs[jj].Nout >> 6) * (jobs[jj].K >> 7)) { bb += (jobs[jj].Nout >> 6) * (jobs[jj].K >> 7); ++jj; } };
;     if (t < total) { locate(t, curj, base); tjob_load(jobs[curj], t - base, v); }
;     while (t < total) {
.LBB0_60:
	s_or_b64 exec, exec, s[6:7]
	v_lshlrev_b32_e32 v0, 4, v160
	v_lshrrev_b32_e32 v32, 3, v160
	v_and_b32_e32 v0, 0x70, v0
	v_lshl_add_u32 v16, v39, 2, 0
	v_mul_u32_u24_e32 v17, 0x204, v38
	v_mul_u32_u24_e32 v18, 0x204, v32
	v_lshlrev_b32_e32 v19, 2, v0
	v_add3_u32 v40, 0, v18, v19
	s_movk_i32 s21, 0x7f
	s_movk_i32 s22, 0xfff
	s_movk_i32 s23, 0x2410
	v_add_u32_e32 v41, v16, v17
	v_lshlrev_b32_e32 v0, 1, v0
	s_mov_b32 s25, s2
	s_waitcnt vmcnt(0)
	s_branch .LBB0_63

; #define LAS __attribute__((address_space(3)))
; __device__ __forceinline__ u32x4 pack8(const float* f) { u32x4 w; w.x = pk2(f[0], f[1]); w.y = pk2(f[2], f[3]); w.z = pk2(f[4], f[5]); w.w = pk2(f[6], f[7]); return w; }
; __device__ __forceinline__ void tjob_store(const TJob& j, int tile, const f32x4 (&v)[4], LAS float* s) {
;     const int tid = threadIdx.x, nkt = j.K >> 7, tn = tile / nkt, tk = tile - tn * nkt;
;     const int nq = tid & 15, kr = tid >> 4;
;     __syncthreads();
; #pragma unroll
;     for (int i = 0; i < 4; ++i)
; #pragma unroll
;         for (int q = 0; q < 4; ++q) s[(4 * nq + q) * 129 + kr + 32 * i] = v[i][q];
;     __syncthreads();
;     const int n = tid >> 3, k16 = (tid & 7) * 16;
;     float f[16];
; #pragma unroll
;     for (int i = 0; i < 16; ++i) f[i] = s[n * 129 + k16 + i];
;     bf16_t* d = j.dst + (size_t)(tn * 64 + n) * j.ld_dst + tk * 128 + k16;
;     *(u32x4*)d = pack8(f); *(u32x4*)(d + 8) = pack8(f + 8);
; }
; __device__ __forceinline__ void transpose_jobs(const TJob* jobs, int njobs, int bi, int nblk, LAS unsigned char* lds) {
;     ...
;         if (tn < total) {
; #pragma unroll
;             for (int i = 0; i < 4; ++i) v[i] = w[i]; }
.LBB0_62:
	s_mul_i32 s13, s13, 40
	s_mul_hi_u32 s14, s12, 40
	s_add_i32 s14, s14, s13
	s_mul_i32 s12, s12, 40
	s_add_u32 s12, s0, s12
	s_addc_u32 s13, s1, s14
	s_barrier
	ds_write2_b32 v41, v33, v4 offset1:32
	ds_write2_b32 v41, v1, v5 offset0:129 offset1:161
	v_add_u32_e32 v1, 0x400, v41
	ds_write2_b32 v1, v2, v6 offset0:2 offset1:34
	ds_write2_b32 v1, v3, v7 offset0:131 offset1:163
	ds_write2_b32 v41, v8, v12 offset0:64 offset1:96
	ds_write2_b32 v41, v9, v13 offset0:193 offset1:225
	ds_write2_b32 v1, v10, v14 offset0:66 offset1:98
	ds_write2_b32 v1, v11, v15 offset0:195 offset1:227
	s_waitcnt lgkmcnt(0)
	s_barrier
	s_load_dword s16, s[12:13], 0xec
	s_load_dwordx2 s[14:15], s[12:13], 0xe0
	s_load_dword s18, s[12:13], 0xf4
	s_sub_i32 s17, s25, s20
	s_abs_i32 s19, s17
	ds_read2_b32 v[2:3], v40 offset1:1
	ds_read2_b32 v[4:5], v40 offset0:2 offset1:3
	ds_read2_b32 v[6:7], v40 offset0:4 offset1:5
	ds_read2_b32 v[8:9], v40 offset0:6 offset1:7
	s_waitcnt lgkmcnt(0)
	s_ashr_i32 s12, s16, 7
	s_abs_i32 s13, s12
	v_cvt_f32_u32_e32 v1, s13
	s_sub_i32 s20, 0, s13
	s_xor_b32 s16, s17, s12
	s_ashr_i32 s16, s16, 31
	v_rcp_iflag_f32_e32 v1, v1
	ds_read2_b32 v[10:11], v40 offset0:8 offset1:9
	ds_read2_b32 v[12:13], v40 offset0:10 offset1:11
	ds_read2_b32 v[14:15], v40 offset0:12 offset1:13
	ds_read2_b32 v[36:37], v40 offset0:14 offset1:15
	v_cvt_pk_bf16_f32 v2, v2, v3
	v_cvt_pk_bf16_f32 v3, v4, v5
	v_mul_f32_e32 v1, 0x4f7ffffe, v1
	v_cvt_u32_f32_e32 v1, v1
	v_cvt_pk_bf16_f32 v4, v6, v7
	v_cvt_pk_bf16_f32 v5, v8, v9
	v_readfirstlane_b32 s25, v1
	s_mul_i32 s20, s20, s25
	s_mul_hi_u32 s20, s25, s20
	s_add_i32 s25, s25, s20
	s_mul_hi_u32 s20, s19, s25
	s_mul_i32 s25, s20, s13
	s_sub_i32 s19, s19, s25
	s_add_i32 s25, s20, 1
	s_sub_i32 s26, s19, s13
	s_cmp_ge_u32 s19, s13
	s_cselect_b32 s20, s25, s20
	s_cselect_b32 s19, s26, s19
	s_add_i32 s25, s20, 1
	s_cmp_ge_u32 s19, s13
	s_cselect_b32 s13, s25, s20
	s_xor_b32 s13, s13, s16
	s_sub_i32 s13, s13, s16
	s_mul_i32 s12, s13, s12
	v_lshl_add_u32 v1, s13, 6, v32
	s_sub_i32 s16, s17, s12
	v_mad_i64_i32 v[42:43], s[12:13], v1, s18, 0
	s_lshl_b32 s12, s16, 7
	v_lshl_add_u64 v[42:43], v[42:43], 1, s[14:15]
	s_ashr_i32 s13, s12, 31
	v_lshl_add_u64 v[42:43], s[12:13], 1, v[42:43]
	v_mov_b32_e32 v1, v35
	v_lshl_add_u64 v[42:43], v[42:43], 0, v[0:1]
	global_store_dwordx4 v[42:43], v[2:5], off
	s_andn2_b64 vcc, exec, s[6:7]
	s_mov_b32 s25, s24
	s_waitcnt lgkmcnt(3)
	v_cvt_pk_bf16_f32 v2, v10, v11
	s_waitcnt lgkmcnt(2)
	v_cvt_pk_bf16_f32 v3, v12, v13
	s_waitcnt lgkmcnt(1)
	v_cvt_pk_bf16_f32 v4, v14, v15
	s_waitcnt lgkmcnt(0)
	v_cvt_pk_bf16_f32 v5, v36, v37
	global_store_dwordx4 v[42:43], v[2:5], off offset:16
	s_mov_b32 s20, s11
	s_waitcnt vmcnt(2)
	v_mov_b32_e32 v33, v20
	v_mov_b32_e32 v1, v21
	v_mov_b32_e32 v2, v22
	v_mov_b32_e32 v3, v23
	v_mov_b32_e32 v4, v16
	v_mov_b32_e32 v5, v17
	v_mov_b32_e32 v6, v18
	v_mov_b32_e32 v7, v19
	v_mov_b32_e32 v8, v28
	v_mov_b32_e32 v9, v29
	v_mov_b32_e32 v10, v30
	v_mov_b32_e32 v11, v31
	v_mov_b32_e32 v12, v24
	v_mov_b32_e32 v13, v25
	v_mov_b32_e32 v14, v26
	v_mov_b32_e32 v15, v27
	s_cbranch_vccz .LBB0_97

; __device__ __forceinline__ void transpose_jobs(const TJob* jobs, int njobs, int bi, int nblk, LAS unsigned char* lds) {
;     ...
;     f32x4 v[4]; int curj = 0, base = 0;
;     int t = bi;
;     auto locate = [&](int tt, int& jj, int& bb) { while (tt >= bb + (jobs[jj].Nout >> 6) * (jobs[jj].K >> 7)) { bb += (jobs[jj].Nout >> 6) * (jobs[jj].K >> 7); ++jj; } };
;     if (t < total) { locate(t, curj, base); tjob_load(jobs[curj], t - base, v); }
;     while (t < total) {
.LBB0_187:
	s_or_b64 exec, exec, s[6:7]
	s_movk_i32 s23, 0x7f
	s_movk_i32 s24, 0xfff
	s_movk_i32 s25, 0x2410
	v_lshlrev_b32_e32 v0, 1, v44
	s_mov_b32 s27, s20
	s_waitcnt vmcnt(0)
	s_branch .LBB0_190

; #define LAS __attribute__((address_space(3)))
; __device__ __forceinline__ u32x4 pack8(const float* f) { u32x4 w; w.x = pk2(f[0], f[1]); w.y = pk2(f[2], f[3]); w.z = pk2(f[4], f[5]); w.w = pk2(f[6], f[7]); return w; }
; __device__ __forceinline__ void tjob_store(const TJob& j, int tile, const f32x4 (&v)[4], LAS float* s) {
;     const int tid = threadIdx.x, nkt = j.K >> 7, tn = tile / nkt, tk = tile - tn * nkt;
;     const int nq = tid & 15, kr = tid >> 4;
;     __syncthreads();
; #pragma unroll
;     for (int i = 0; i < 4; ++i)
; #pragma unroll
;         for (int q = 0; q < 4; ++q) s[(4 * nq + q) * 129 + kr + 32 * i] = v[i][q];
;     __syncthreads();
;     const int n = tid >> 3, k16 = (tid & 7) * 16;
;     float f[16];
; #pragma unroll
;     for (int i = 0; i < 16; ++i) f[i] = s[n * 129 + k16 + i];
;     bf16_t* d = j.dst + (size_t)(tn * 64 + n) * j.ld_dst + tk * 128 + k16;
;     *(u32x4*)d = pack8(f); *(u32x4*)(d + 8) = pack8(f + 8);
; }
; __device__ __forceinline__ void transpose_jobs(const TJob* jobs, int njobs, int bi, int nblk, LAS unsigned char* lds) {
;     ...
;         if (tn < total) {
; #pragma unroll
;             for (int i = 0; i < 4; ++i) v[i] = w[i]; }
.LBB0_189:
	s_mul_i32 s13, s13, 40
	s_mul_hi_u32 s14, s12, 40
	s_add_i32 s14, s14, s13
	s_mul_i32 s12, s12, 40
	s_add_u32 s12, s0, s12
	v_add_u32_e32 v32, v41, v42
	s_addc_u32 s13, s1, s14
	s_barrier
	ds_write2_b32 v32, v33, v4 offset1:32
	ds_write2_b32 v32, v1, v5 offset0:129 offset1:161
	v_add_u32_e32 v1, 0x400, v32
	ds_write2_b32 v1, v2, v6 offset0:2 offset1:34
	ds_write2_b32 v1, v3, v7 offset0:131 offset1:163
	ds_write2_b32 v32, v8, v12 offset0:64 offset1:96
	ds_write2_b32 v32, v9, v13 offset0:193 offset1:225
	ds_write2_b32 v1, v10, v14 offset0:66 offset1:98
	ds_write2_b32 v1, v11, v15 offset0:195 offset1:227
	s_waitcnt lgkmcnt(0)
	s_barrier
	s_load_dword s16, s[12:13], 0x114
	s_load_dwordx2 s[14:15], s[12:13], 0x108
	s_load_dword s18, s[12:13], 0x11c
	s_sub_i32 s17, s27, s22
	s_abs_i32 s19, s17
	ds_read2_b32 v[2:3], v43 offset1:1
	ds_read2_b32 v[4:5], v43 offset0:2 offset1:3
	ds_read2_b32 v[6:7], v43 offset0:4 offset1:5
	ds_read2_b32 v[8:9], v43 offset0:6 offset1:7
	s_waitcnt lgkmcnt(0)
	s_ashr_i32 s12, s16, 7
	s_abs_i32 s13, s12
	v_cvt_f32_u32_e32 v1, s13
	s_sub_i32 s22, 0, s13
	s_xor_b32 s16, s17, s12
	s_ashr_i32 s16, s16, 31
	v_rcp_iflag_f32_e32 v1, v1
	ds_read2_b32 v[10:11], v43 offset0:8 offset1:9
	ds_read2_b32 v[12:13], v43 offset0:10 offset1:11
	ds_read2_b32 v[14:15], v43 offset0:12 offset1:13
	ds_read2_b32 v[32:33], v43 offset0:14 offset1:15
	v_cvt_pk_bf16_f32 v2, v2, v3
	v_cvt_pk_bf16_f32 v3, v4, v5
	v_mul_f32_e32 v1, 0x4f7ffffe, v1
	v_cvt_u32_f32_e32 v1, v1
	v_cvt_pk_bf16_f32 v4, v6, v7
	v_cvt_pk_bf16_f32 v5, v8, v9
	v_readfirstlane_b32 s27, v1
	s_mul_i32 s22, s22, s27
	s_mul_hi_u32 s22, s27, s22
	s_add_i32 s27, s27, s22
	s_mul_hi_u32 s22, s19, s27
	s_mul_i32 s27, s22, s13
	s_sub_i32 s19, s19, s27
	s_add_i32 s27, s22, 1
	s_sub_i32 s28, s19, s13
	s_cmp_ge_u32 s19, s13
	s_cselect_b32 s22, s27, s22
	s_cselect_b32 s19, s28, s19
	s_add_i32 s27, s22, 1
	s_cmp_ge_u32 s19, s13
	s_cselect_b32 s13, s27, s22
	s_xor_b32 s13, s13, s16
	s_sub_i32 s13, s13, s16
	s_mul_i32 s12, s13, s12
	v_lshl_add_u32 v1, s13, 6, v38
	s_sub_i32 s16, s17, s12
	v_mad_i64_i32 v[36:37], s[12:13], v1, s18, 0
	s_lshl_b32 s12, s16, 7
	v_lshl_add_u64 v[36:37], v[36:37], 1, s[14:15]
	s_ashr_i32 s13, s12, 31
	v_lshl_add_u64 v[36:37], s[12:13], 1, v[36:37]
	v_mov_b32_e32 v1, v35
	v_lshl_add_u64 v[36:37], v[36:37], 0, v[0:1]
	global_store_dwordx4 v[36:37], v[2:5], off
	s_andn2_b64 vcc, exec, s[6:7]
	s_mov_b32 s27, s26
	s_waitcnt lgkmcnt(3)
	v_cvt_pk_bf16_f32 v2, v10, v11
	s_waitcnt lgkmcnt(2)
	v_cvt_pk_bf16_f32 v3, v12, v13
	s_waitcnt lgkmcnt(1)
	v_cvt_pk_bf16_f32 v4, v14, v15
	s_waitcnt lgkmcnt(0)
	v_cvt_pk_bf16_f32 v5, v32, v33
	global_store_dwordx4 v[36:37], v[2:5], off offset:16
	s_mov_b32 s22, s11
	s_waitcnt vmcnt(2)
	v_mov_b32_e32 v6, v18
	v_mov_b32_e32 v33, v20
	v_mov_b32_e32 v1, v21
	v_mov_b32_e32 v2, v22
	v_mov_b32_e32 v3, v23
	v_mov_b32_e32 v4, v16
	v_mov_b32_e32 v5, v17
	v_mov_b32_e32 v7, v19
	v_mov_b32_e32 v8, v28
	v_mov_b32_e32 v9, v29
	v_mov_b32_e32 v10, v30
	v_mov_b32_e32 v11, v31
	v_mov_b32_e32 v12, v24
	v_mov_b32_e32 v13, v25
	v_mov_b32_e32 v14, v26
	v_mov_b32_e32 v15, v27
	s_cbranch_vccz .LBB0_224

; __device__ __forceinline__ void transpose_jobs(const TJob* jobs, int njobs, int bi, int nblk, LAS unsigned char* lds) {
;     ...
;     f32x4 v[4]; int curj = 0, base = 0;
;     int t = bi;
;     auto locate = [&](int tt, int& jj, int& bb) { while (tt >= bb + (jobs[jj].Nout >> 6) * (jobs[jj].K >> 7)) { bb += (jobs[jj].Nout >> 6) * (jobs[jj].K >> 7); ++jj; } };
;     if (t < total) { locate(t, curj, base); tjob_load(jobs[curj], t - base, v); }
;     while (t < total) {
.LBB0_257:
	s_or_b64 exec, exec, s[6:7]
	s_movk_i32 s23, 0x7f
	s_movk_i32 s24, 0xfff
	s_movk_i32 s25, 0x2410
	v_lshlrev_b32_e32 v0, 1, v44
	s_waitcnt vmcnt(0)
	s_branch .LBB0_260

; #define LAS __attribute__((address_space(3)))
; __device__ __forceinline__ u32x4 pack8(const float* f) { u32x4 w; w.x = pk2(f[0], f[1]); w.y = pk2(f[2], f[3]); w.z = pk2(f[4], f[5]); w.w = pk2(f[6], f[7]); return w; }
; __device__ __forceinline__ void tjob_store(const TJob& j, int tile, const f32x4 (&v)[4], LAS float* s) {
;     const int tid = threadIdx.x, nkt = j.K >> 7, tn = tile / nkt, tk = tile - tn * nkt;
;     const int nq = tid & 15, kr = tid >> 4;
;     __syncthreads();
; #pragma unroll
;     for (int i = 0; i < 4; ++i)
; #pragma unroll
;         for (int q = 0; q < 4; ++q) s[(4 * nq + q) * 129 + kr + 32 * i] = v[i][q];
;     __syncthreads();
;     const int n = tid >> 3, k16 = (tid & 7) * 16;
;     float f[16];
; #pragma unroll
;     for (int i = 0; i < 16; ++i) f[i] = s[n * 129 + k16 + i];
;     bf16_t* d = j.dst + (size_t)(tn * 64 + n) * j.ld_dst + tk * 128 + k16;
;     *(u32x4*)d = pack8(f); *(u32x4*)(d + 8) = pack8(f + 8);
; }
; __device__ __forceinline__ void transpose_jobs(const TJob* jobs, int njobs, int bi, int nblk, LAS unsigned char* lds) {
;     ...
;         if (tn < total) {
; #pragma unroll
;             for (int i = 0; i < 4; ++i) v[i] = w[i]; }
.LBB0_259:
	s_mul_i32 s13, s13, 40
	s_mul_hi_u32 s14, s12, 40
	s_add_i32 s14, s14, s13
	s_mul_i32 s12, s12, 40
	s_add_u32 s12, s0, s12
	v_add_u32_e32 v32, v41, v42
	s_addc_u32 s13, s1, s14
	s_barrier
	ds_write2_b32 v32, v33, v4 offset1:32
	ds_write2_b32 v32, v1, v5 offset0:129 offset1:161
	v_add_u32_e32 v1, 0x400, v32
	ds_write2_b32 v1, v2, v6 offset0:2 offset1:34
	ds_write2_b32 v1, v3, v7 offset0:131 offset1:163
	ds_write2_b32 v32, v8, v12 offset0:64 offset1:96
	ds_write2_b32 v32, v9, v13 offset0:193 offset1:225
	ds_write2_b32 v1, v10, v14 offset0:66 offset1:98
	ds_write2_b32 v1, v11, v15 offset0:195 offset1:227
	s_waitcnt lgkmcnt(0)
	s_barrier
	s_load_dword s16, s[12:13], 0x18c
	s_load_dwordx2 s[14:15], s[12:13], 0x180
	s_load_dword s18, s[12:13], 0x194
	s_sub_i32 s17, s20, s22
	s_abs_i32 s19, s17
	ds_read2_b32 v[2:3], v43 offset1:1
	ds_read2_b32 v[4:5], v43 offset0:2 offset1:3
	ds_read2_b32 v[6:7], v43 offset0:4 offset1:5
	ds_read2_b32 v[8:9], v43 offset0:6 offset1:7
	s_waitcnt lgkmcnt(0)
	s_ashr_i32 s12, s16, 7
	s_abs_i32 s13, s12
	v_cvt_f32_u32_e32 v1, s13
	s_sub_i32 s20, 0, s13
	s_xor_b32 s16, s17, s12
	s_ashr_i32 s16, s16, 31
	v_rcp_iflag_f32_e32 v1, v1
	ds_read2_b32 v[10:11], v43 offset0:8 offset1:9
	ds_read2_b32 v[12:13], v43 offset0:10 offset1:11
	ds_read2_b32 v[14:15], v43 offset0:12 offset1:13
	ds_read2_b32 v[32:33], v43 offset0:14 offset1:15
	v_cvt_pk_bf16_f32 v2, v2, v3
	v_cvt_pk_bf16_f32 v3, v4, v5
	v_mul_f32_e32 v1, 0x4f7ffffe, v1
	v_cvt_u32_f32_e32 v1, v1
	v_cvt_pk_bf16_f32 v4, v6, v7
	v_cvt_pk_bf16_f32 v5, v8, v9
	v_readfirstlane_b32 s22, v1
	s_mul_i32 s20, s20, s22
	s_mul_hi_u32 s20, s22, s20
	s_add_i32 s22, s22, s20
	s_mul_hi_u32 s20, s19, s22
	s_mul_i32 s22, s20, s13
	s_sub_i32 s19, s19, s22
	s_add_i32 s22, s20, 1
	s_sub_i32 s27, s19, s13
	s_cmp_ge_u32 s19, s13
	s_cselect_b32 s20, s22, s20
	s_cselect_b32 s19, s27, s19
	s_add_i32 s22, s20, 1
	s_cmp_ge_u32 s19, s13
	s_cselect_b32 s13, s22, s20
	s_xor_b32 s13, s13, s16
	s_sub_i32 s13, s13, s16
	s_mul_i32 s12, s13, s12
	v_lshl_add_u32 v1, s13, 6, v38
	s_sub_i32 s16, s17, s12
	v_mad_i64_i32 v[36:37], s[12:13], v1, s18, 0
	s_lshl_b32 s12, s16, 7
	v_lshl_add_u64 v[36:37], v[36:37], 1, s[14:15]
	s_ashr_i32 s13, s12, 31
	v_lshl_add_u64 v[36:37], s[12:13], 1, v[36:37]
	v_mov_b32_e32 v1, v35
	v_lshl_add_u64 v[36:37], v[36:37], 0, v[0:1]
	global_store_dwordx4 v[36:37], v[2:5], off
	s_andn2_b64 vcc, exec, s[6:7]
	s_mov_b32 s20, s26
	s_waitcnt lgkmcnt(3)
	v_cvt_pk_bf16_f32 v2, v10, v11
	s_waitcnt lgkmcnt(2)
	v_cvt_pk_bf16_f32 v3, v12, v13
	s_waitcnt lgkmcnt(1)
	v_cvt_pk_bf16_f32 v4, v14, v15
	s_waitcnt lgkmcnt(0)
	v_cvt_pk_bf16_f32 v5, v32, v33
	global_store_dwordx4 v[36:37], v[2:5], off offset:16
	s_mov_b32 s22, s11
	s_waitcnt vmcnt(2)
	v_mov_b32_e32 v6, v18
	v_mov_b32_e32 v33, v20
	v_mov_b32_e32 v1, v21
	v_mov_b32_e32 v2, v22
	v_mov_b32_e32 v3, v23
	v_mov_b32_e32 v4, v16
	v_mov_b32_e32 v5, v17
	v_mov_b32_e32 v7, v19
	v_mov_b32_e32 v8, v28
	v_mov_b32_e32 v9, v29
	v_mov_b32_e32 v10, v30
	v_mov_b32_e32 v11, v31
	v_mov_b32_e32 v12, v24
	v_mov_b32_e32 v13, v25
	v_mov_b32_e32 v14, v26
	v_mov_b32_e32 v15, v27
	s_cbranch_vccz .LBB0_294

; __device__ __forceinline__ u32x4 pack8(const float* f) { u32x4 w; w.x = pk2(f[0], f[1]); w.y = pk2(f[2], f[3]); w.z = pk2(f[4], f[5]); w.w = pk2(f[6], f[7]); return w; }
; template <int NTOK, bool SMP>
; __device__ __forceinline__ void mixer_item(const Params& p, int it) {
;     ...
;         const int pc = (tid - 384) * 8, gi = pc >> 8, w = 2 << gi;
;         const int seqrow0 = SMP ? TP + sb * 4 : b * 2048;
;         const float* sp = p.in[6] + (size_t)sb * 15 * 1024 + pc;
;         auto xpool = [&](int tt, float* f) {
;             if (tt >= 0) unpack8(*(const u32x4*)(proj + (size_t)(seqrow0 + tt) * NPROJ + C_XP + pc), f);
;             else if (SMP) { const float* s = sp + (size_t)(15 + tt) * 1024;
; #pragma unroll
;                 for (int i = 0; i < 8; ++i) f[i] = s[i]; }
;             else {
; #pragma unroll
;                 for (int i = 0; i < 8; ++i) f[i] = 0.f; }
;         };
;         float s[8];
; #pragma unroll
;         for (int i = 0; i < 8; ++i) s[i] = 0.f;
; #pragma unroll
;         for (int q = 1; q < 16; ++q) if (q < w) { float f[8]; xpool(t0 - q, f);
; #pragma unroll
;             for (int i = 0; i < 8; ++i) s[i] += f[i]; }
; #pragma unroll 4
;         for (int t = 0; t < NTOK; ++t) {
;             const int tt = t0 + t; float x[8], y[8], f[8];
;             xpool(tt, x);
;             const float cnt = SMP ? (float)w : (float)min(w, tt + 1); const float ic = 1.0f / cnt;
; #pragma unroll
;             for (int i = 0; i < 8; ++i) { s[i] += x[i]; y[i] = s[i] * ic - x[i]; }
;             *(u32x4*)(yp + (size_t)(seqrow0 + tt) * 1024 + pc) = pack8(y);
;             xpool(tt - w + 1, f);
; #pragma unroll
;             for (int i = 0; i < 8; ++i) s[i] -= f[i];
;             if (SMP) { float* o = p.out + O_PS + ((size_t)sb * 15 + 11 + t) * 1024 + pc; *(f32x4*)o = (f32x4){x[0], x[1], x[2], x[3]}; *(f32x4*)(o + 4) = (f32x4){x[4], x[5], x[6], x[7]}; }
.LBB0_818:
	s_or_b64 exec, exec, s[22:23]
	s_and_saveexec_b64 s[22:23], s[10:11]
	s_xor_b64 s[60:61], exec, s[22:23]
	s_cbranch_execz .LBB0_833
	v_readfirstlane_b32 s22, v160
	s_cmpk_ge_u32 s22, 0x1c0
	s_cbranch_scc1 .Lps_w7
	s_load_dwordx2 s[74:75], s[0:1], 0x30
	s_mov_b32 s72, 0
	s_mov_b32 s73, -1
	s_mov_b64 s[76:77], exec
	s_andn2_b64 s[78:79], exec, s[72:73]
	v_lshlrev_b32_e32 v185, 1, v82
	s_mul_i32 s66, s64, 15
	s_mov_b32 s67, 0
	s_lshl_b64 s[66:67], s[66:67], 12
	s_waitcnt lgkmcnt(0)
	s_add_u32 s74, s74, s66
	s_addc_u32 s75, s75, s67
	s_add_u32 s66, s66, s24
	s_addc_u32 s67, s67, s25
	s_add_u32 s66, s66, 0x8ae0000
	s_addc_u32 s67, s67, 0
	s_add_u32 s68, s74, 0xe000
	s_addc_u32 s69, s75, 0
	global_load_dwordx4 v[8:11], v185, s[68:69]
	global_load_dwordx4 v[4:7], v185, s[68:69] offset:16
	s_sub_u32 s68, s68, 0x1000
	s_subb_u32 s69, s69, 0
	global_load_dwordx4 v[12:15], v185, s[68:69]
	global_load_dwordx4 v[16:19], v185, s[68:69] offset:16
	s_sub_u32 s68, s68, 0x1000
	s_subb_u32 s69, s69, 0
	global_load_dwordx4 v[20:23], v185, s[68:69]
	global_load_dwordx4 v[24:27], v185, s[68:69] offset:16
	s_sub_u32 s68, s68, 0x1000
	s_subb_u32 s69, s69, 0
	global_load_dwordx4 v[28:31], v185, s[68:69]
	global_load_dwordx4 v[32:35], v185, s[68:69] offset:16
	s_sub_u32 s68, s68, 0x1000
	s_subb_u32 s69, s69, 0
	global_load_dwordx4 v[36:39], v185, s[68:69]
	global_load_dwordx4 v[40:43], v185, s[68:69] offset:16
	s_sub_u32 s68, s68, 0x1000
	s_subb_u32 s69, s69, 0
	global_load_dwordx4 v[44:47], v185, s[68:69]
	global_load_dwordx4 v[48:51], v185, s[68:69] offset:16
	s_sub_u32 s68, s68, 0x1000
	s_subb_u32 s69, s69, 0
	global_load_dwordx4 v[52:55], v185, s[68:69]
	global_load_dwordx4 v[56:59], v185, s[68:69] offset:16
	s_sub_u32 s68, s68, 0x1000
	s_subb_u32 s69, s69, 0
	global_load_dwordx4 v[60:63], v185, s[68:69]
	global_load_dwordx4 v[130:133], v185, s[68:69] offset:16
	s_sub_u32 s68, s68, 0x1000
	s_subb_u32 s69, s69, 0
	global_load_dwordx4 v[134:137], v185, s[68:69]
	global_load_dwordx4 v[138:141], v185, s[68:69] offset:16
	s_sub_u32 s68, s68, 0x1000
	s_subb_u32 s69, s69, 0
	global_load_dwordx4 v[142:145], v185, s[68:69]
	global_load_dwordx4 v[146:149], v185, s[68:69] offset:16
	s_sub_u32 s68, s68, 0x1000
	s_subb_u32 s69, s69, 0
	global_load_dwordx4 v[150:153], v185, s[68:69]
	global_load_dwordx4 v[156:159], v185, s[68:69] offset:16
	s_mul_i32 s70, s65, 0x4a00
	s_mul_hi_u32 s71, s65, 0x4a00
	s_add_u32 s70, s70, s30
	s_addc_u32 s71, s71, s31
	s_add_u32 s70, s70, 0x2000
	s_addc_u32 s71, s71, 0
	global_load_dwordx4 v[162:165], v82, s[70:71]
	s_add_u32 s70, s70, 0x4a00
	s_addc_u32 s71, s71, 0
	global_load_dwordx4 v[186:189], v82, s[70:71]
	s_add_u32 s70, s70, 0x4a00
	s_addc_u32 s71, s71, 0
	global_load_dwordx4 v[190:193], v82, s[70:71]
	s_add_u32 s70, s70, 0x4a00
	s_addc_u32 s71, s71, 0
	global_load_dwordx4 v[194:197], v82, s[70:71]
	s_lshl_b32 s70, s65, 11
	s_add_u32 s70, s70, s26
	s_addc_u32 s71, s27, 0
	s_add_u32 s70, s70, 0xd439000
	s_addc_u32 s71, s71, 0
	s_waitcnt vmcnt(24)
	v_pk_add_f32 v[198:199], v[8:9], 0 op_sel_hi:[1,0]
	v_pk_add_f32 v[200:201], v[10:11], 0 op_sel_hi:[1,0]
	v_pk_add_f32 v[202:203], v[4:5], 0 op_sel_hi:[1,0]
	v_pk_add_f32 v[204:205], v[6:7], 0 op_sel_hi:[1,0]
	s_mov_b64 exec, s[72:73]
	s_waitcnt vmcnt(22)
	v_pk_add_f32 v[198:199], v[198:199], v[12:13]
	v_pk_add_f32 v[200:201], v[200:201], v[14:15]
	v_pk_add_f32 v[202:203], v[202:203], v[16:17]
	v_pk_add_f32 v[204:205], v[204:205], v[18:19]
	s_waitcnt vmcnt(20)
	v_pk_add_f32 v[198:199], v[198:199], v[20:21]
	v_pk_add_f32 v[200:201], v[200:201], v[22:23]
	v_pk_add_f32 v[202:203], v[202:203], v[24:25]
	v_pk_add_f32 v[204:205], v[204:205], v[26:27]
	s_mov_b64 exec, s[76:77]
	s_waitcnt vmcnt(3)
	v_lshlrev_b32_e32 v206, 16, v162
	v_and_b32_e32 v207, 0xffff0000, v162
	v_lshlrev_b32_e32 v208, 16, v163
	v_and_b32_e32 v209, 0xffff0000, v163
	v_lshlrev_b32_e32 v210, 16, v164
	v_and_b32_e32 v211, 0xffff0000, v164
	v_lshlrev_b32_e32 v212, 16, v165
	v_and_b32_e32 v213, 0xffff0000, v165
	v_pk_add_f32 v[198:199], v[198:199], v[206:207]
	v_pk_fma_f32 v[222:223], v[72:73], v[198:199], v[206:207] neg_lo:[0,0,1] neg_hi:[0,0,1]
	v_cvt_pk_bf16_f32 v0, v222, v223
	v_pk_add_f32 v[200:201], v[200:201], v[208:209]
	v_pk_fma_f32 v[222:223], v[72:73], v[200:201], v[208:209] neg_lo:[0,0,1] neg_hi:[0,0,1]
	v_cvt_pk_bf16_f32 v1, v222, v223
	v_pk_add_f32 v[202:203], v[202:203], v[210:211]
	v_pk_fma_f32 v[222:223], v[72:73], v[202:203], v[210:211] neg_lo:[0,0,1] neg_hi:[0,0,1]
	v_cvt_pk_bf16_f32 v2, v222, v223
	v_pk_add_f32 v[204:205], v[204:205], v[212:213]
	v_pk_fma_f32 v[222:223], v[72:73], v[204:205], v[212:213] neg_lo:[0,0,1] neg_hi:[0,0,1]
	v_cvt_pk_bf16_f32 v3, v222, v223
	global_store_dwordx4 v82, v[0:3], s[70:71]
	s_add_u32 s68, s66, 0xb000
	s_addc_u32 s69, s67, 0
	global_store_dwordx4 v185, v[206:209], s[68:69]
	global_store_dwordx4 v185, v[210:213], s[68:69] offset:16
	s_mov_b64 exec, s[78:79]
	v_pk_add_f32 v[198:199], v[198:199], v[8:9] neg_lo:[0,1] neg_hi:[0,1]
	v_pk_add_f32 v[200:201], v[200:201], v[10:11] neg_lo:[0,1] neg_hi:[0,1]
	v_pk_add_f32 v[202:203], v[202:203], v[4:5] neg_lo:[0,1] neg_hi:[0,1]
	v_pk_add_f32 v[204:205], v[204:205], v[6:7] neg_lo:[0,1] neg_hi:[0,1]
	s_mov_b64 exec, s[72:73]
	v_pk_add_f32 v[198:199], v[198:199], v[20:21] neg_lo:[0,1] neg_hi:[0,1]
	v_pk_add_f32 v[200:201], v[200:201], v[22:23] neg_lo:[0,1] neg_hi:[0,1]
	v_pk_add_f32 v[202:203], v[202:203], v[24:25] neg_lo:[0,1] neg_hi:[0,1]
	v_pk_add_f32 v[204:205], v[204:205], v[26:27] neg_lo:[0,1] neg_hi:[0,1]
	s_mov_b64 exec, s[76:77]
	s_waitcnt vmcnt(5)
; __device__ __forceinline__ u32x4 pack8(const float* f) { u32x4 w; w.x = pk2(f[0], f[1]); w.y = pk2(f[2], f[3]); w.z = pk2(f[4], f[5]); w.w = pk2(f[6], f[7]); return w; }
; template <int NTOK, bool SMP>
; __device__ __forceinline__ void mixer_item(const Params& p, int it) {
;     ...
;         for (int t = 0; t < NTOK; ++t) {
;             const int tt = t0 + t; float x[8], y[8], f[8];
;             xpool(tt, x);
;             const float cnt = SMP ? (float)w : (float)min(w, tt + 1); const float ic = 1.0f / cnt;
; #pragma unroll
;             for (int i = 0; i < 8; ++i) { s[i] += x[i]; y[i] = s[i] * ic - x[i]; }
;             *(u32x4*)(yp + (size_t)(seqrow0 + tt) * 1024 + pc) = pack8(y);
;             xpool(tt - w + 1, f);
; #pragma unroll
;             for (int i = 0; i < 8; ++i) s[i] -= f[i];
;             if (SMP) { float* o = p.out + O_PS + ((size_t)sb * 15 + 11 + t) * 1024 + pc; *(f32x4*)o = (f32x4){x[0], x[1], x[2], x[3]}; *(f32x4*)(o + 4) = (f32x4){x[4], x[5], x[6], x[7]}; }
	v_lshlrev_b32_e32 v214, 16, v186
	v_and_b32_e32 v215, 0xffff0000, v186
	v_lshlrev_b32_e32 v216, 16, v187
	v_and_b32_e32 v217, 0xffff0000, v187
	v_lshlrev_b32_e32 v218, 16, v188
	v_and_b32_e32 v219, 0xffff0000, v188
	v_lshlrev_b32_e32 v220, 16, v189
	v_and_b32_e32 v221, 0xffff0000, v189
	v_pk_add_f32 v[198:199], v[198:199], v[214:215]
	v_pk_fma_f32 v[222:223], v[72:73], v[198:199], v[214:215] neg_lo:[0,0,1] neg_hi:[0,0,1]
	v_cvt_pk_bf16_f32 v226, v222, v223
	v_pk_add_f32 v[200:201], v[200:201], v[216:217]
	v_pk_fma_f32 v[222:223], v[72:73], v[200:201], v[216:217] neg_lo:[0,0,1] neg_hi:[0,0,1]
	v_cvt_pk_bf16_f32 v227, v222, v223
	v_pk_add_f32 v[202:203], v[202:203], v[218:219]
	v_pk_fma_f32 v[222:223], v[72:73], v[202:203], v[218:219] neg_lo:[0,0,1] neg_hi:[0,0,1]
	v_cvt_pk_bf16_f32 v228, v222, v223
	v_pk_add_f32 v[204:205], v[204:205], v[220:221]
	v_pk_fma_f32 v[222:223], v[72:73], v[204:205], v[220:221] neg_lo:[0,0,1] neg_hi:[0,0,1]
	v_cvt_pk_bf16_f32 v229, v222, v223
	s_add_u32 s70, s70, 0x800
	s_addc_u32 s71, s71, 0
	global_store_dwordx4 v82, v[226:229], s[70:71]
	s_add_u32 s68, s66, 0xc000
	s_addc_u32 s69, s67, 0
	global_store_dwordx4 v185, v[214:217], s[68:69]
	global_store_dwordx4 v185, v[218:221], s[68:69] offset:16
	s_mov_b64 exec, s[78:79]
	v_lshlrev_b32_e32 v222, 16, v162
	v_and_b32_e32 v223, 0xffff0000, v162
	v_pk_add_f32 v[198:199], v[198:199], v[222:223] neg_lo:[0,1] neg_hi:[0,1]
	v_lshlrev_b32_e32 v222, 16, v163
	v_and_b32_e32 v223, 0xffff0000, v163
	v_pk_add_f32 v[200:201], v[200:201], v[222:223] neg_lo:[0,1] neg_hi:[0,1]
	v_lshlrev_b32_e32 v222, 16, v164
	v_and_b32_e32 v223, 0xffff0000, v164
	v_pk_add_f32 v[202:203], v[202:203], v[222:223] neg_lo:[0,1] neg_hi:[0,1]
	v_lshlrev_b32_e32 v222, 16, v165
	v_and_b32_e32 v223, 0xffff0000, v165
	v_pk_add_f32 v[204:205], v[204:205], v[222:223] neg_lo:[0,1] neg_hi:[0,1]
	s_mov_b64 exec, s[72:73]
	v_pk_add_f32 v[198:199], v[198:199], v[12:13] neg_lo:[0,1] neg_hi:[0,1]
	v_pk_add_f32 v[200:201], v[200:201], v[14:15] neg_lo:[0,1] neg_hi:[0,1]
	v_pk_add_f32 v[202:203], v[202:203], v[16:17] neg_lo:[0,1] neg_hi:[0,1]
	v_pk_add_f32 v[204:205], v[204:205], v[18:19] neg_lo:[0,1] neg_hi:[0,1]
	s_mov_b64 exec, s[76:77]
	s_waitcnt vmcnt(7)
	v_lshlrev_b32_e32 v206, 16, v190
	v_and_b32_e32 v207, 0xffff0000, v190
	v_lshlrev_b32_e32 v208, 16, v191
	v_and_b32_e32 v209, 0xffff0000, v191
	v_lshlrev_b32_e32 v210, 16, v192
	v_and_b32_e32 v211, 0xffff0000, v192
	v_lshlrev_b32_e32 v212, 16, v193
	v_and_b32_e32 v213, 0xffff0000, v193
	v_pk_add_f32 v[198:199], v[198:199], v[206:207]
	v_pk_fma_f32 v[222:223], v[72:73], v[198:199], v[206:207] neg_lo:[0,0,1] neg_hi:[0,0,1]
	v_cvt_pk_bf16_f32 v0, v222, v223
	v_pk_add_f32 v[200:201], v[200:201], v[208:209]
	v_pk_fma_f32 v[222:223], v[72:73], v[200:201], v[208:209] neg_lo:[0,0,1] neg_hi:[0,0,1]
	v_cvt_pk_bf16_f32 v1, v222, v223
	v_pk_add_f32 v[202:203], v[202:203], v[210:211]
	v_pk_fma_f32 v[222:223], v[72:73], v[202:203], v[210:211] neg_lo:[0,0,1] neg_hi:[0,0,1]
	v_cvt_pk_bf16_f32 v2, v222, v223
	v_pk_add_f32 v[204:205], v[204:205], v[212:213]
	v_pk_fma_f32 v[222:223], v[72:73], v[204:205], v[212:213] neg_lo:[0,0,1] neg_hi:[0,0,1]
	v_cvt_pk_bf16_f32 v3, v222, v223
	s_add_u32 s70, s70, 0x800
	s_addc_u32 s71, s71, 0
	global_store_dwordx4 v82, v[0:3], s[70:71]
	s_add_u32 s68, s66, 0xd000
	s_addc_u32 s69, s67, 0
	global_store_dwordx4 v185, v[206:209], s[68:69]
	global_store_dwordx4 v185, v[210:213], s[68:69] offset:16
	s_mov_b64 exec, s[78:79]
	v_lshlrev_b32_e32 v222, 16, v186
	v_and_b32_e32 v223, 0xffff0000, v186
	v_pk_add_f32 v[198:199], v[198:199], v[222:223] neg_lo:[0,1] neg_hi:[0,1]
	v_lshlrev_b32_e32 v222, 16, v187
	v_and_b32_e32 v223, 0xffff0000, v187
	v_pk_add_f32 v[200:201], v[200:201], v[222:223] neg_lo:[0,1] neg_hi:[0,1]
	v_lshlrev_b32_e32 v222, 16, v188
	v_and_b32_e32 v223, 0xffff0000, v188
	v_pk_add_f32 v[202:203], v[202:203], v[222:223] neg_lo:[0,1] neg_hi:[0,1]
	v_lshlrev_b32_e32 v222, 16, v189
	v_and_b32_e32 v223, 0xffff0000, v189
	v_pk_add_f32 v[204:205], v[204:205], v[222:223] neg_lo:[0,1] neg_hi:[0,1]
	s_mov_b64 exec, s[72:73]
	v_pk_add_f32 v[198:199], v[198:199], v[8:9] neg_lo:[0,1] neg_hi:[0,1]
	v_pk_add_f32 v[200:201], v[200:201], v[10:11] neg_lo:[0,1] neg_hi:[0,1]
	v_pk_add_f32 v[202:203], v[202:203], v[4:5] neg_lo:[0,1] neg_hi:[0,1]
	v_pk_add_f32 v[204:205], v[204:205], v[6:7] neg_lo:[0,1] neg_hi:[0,1]
	s_mov_b64 exec, s[76:77]
	s_waitcnt vmcnt(9)
; __device__ __forceinline__ u32x4 pack8(const float* f) { u32x4 w; w.x = pk2(f[0], f[1]); w.y = pk2(f[2], f[3]); w.z = pk2(f[4], f[5]); w.w = pk2(f[6], f[7]); return w; }
; template <int NTOK, bool SMP>
; __device__ __forceinline__ void mixer_item(const Params& p, int it) {
;     ...
;         const int pc = (tid - 384) * 8, gi = pc >> 8, w = 2 << gi;
;         const int seqrow0 = SMP ? TP + sb * 4 : b * 2048;
;         const float* sp = p.in[6] + (size_t)sb * 15 * 1024 + pc;
;         auto xpool = [&](int tt, float* f) {
;             if (tt >= 0) unpack8(*(const u32x4*)(proj + (size_t)(seqrow0 + tt) * NPROJ + C_XP + pc), f);
;             else if (SMP) { const float* s = sp + (size_t)(15 + tt) * 1024;
; #pragma unroll
;                 for (int i = 0; i < 8; ++i) f[i] = s[i]; }
;             else {
; #pragma unroll
;                 for (int i = 0; i < 8; ++i) f[i] = 0.f; }
;         };
;         float s[8];
; #pragma unroll
;         for (int i = 0; i < 8; ++i) s[i] = 0.f;
; #pragma unroll
;         for (int q = 1; q < 16; ++q) if (q < w) { float f[8]; xpool(t0 - q, f);
; #pragma unroll
;             for (int i = 0; i < 8; ++i) s[i] += f[i]; }
;     ...
;         for (int t = 0; t < NTOK; ++t) {
;             const int tt = t0 + t; float x[8], y[8], f[8];
;             xpool(tt, x);
;             const float cnt = SMP ? (float)w : (float)min(w, tt + 1); const float ic = 1.0f / cnt;
; #pragma unroll
;             for (int i = 0; i < 8; ++i) { s[i] += x[i]; y[i] = s[i] * ic - x[i]; }
;             *(u32x4*)(yp + (size_t)(seqrow0 + tt) * 1024 + pc) = pack8(y);
;             xpool(tt - w + 1, f);
; #pragma unroll
;             for (int i = 0; i < 8; ++i) s[i] -= f[i];
;             if (SMP) { float* o = p.out + O_PS + ((size_t)sb * 15 + 11 + t) * 1024 + pc; *(f32x4*)o = (f32x4){x[0], x[1], x[2], x[3]}; *(f32x4*)(o + 4) = (f32x4){x[4], x[5], x[6], x[7]}; }
;             else if (tt >= 2033) { float* o = p.out + O_PP + ((size_t)b * 15 + (tt - 2033)) * 1024 + pc; *(f32x4*)o = (f32x4){x[0], x[1], x[2], x[3]}; *(f32x4*)(o + 4) = (f32x4){x[4], x[5], x[6], x[7]}; }
;         }
;         if (SMP) {
; #pragma unroll
;             for (int r = 0; r < 11; ++r) { const float* s2 = sp + (size_t)(4 + r) * 1024; float* o = p.out + O_PS + ((size_t)sb * 15 + r) * 1024 + pc; *(f32x4*)o = *(const f32x4*)s2; *(f32x4*)(o + 4) = *(const f32x4*)(s2 + 4); } }
	v_lshlrev_b32_e32 v214, 16, v194
	v_and_b32_e32 v215, 0xffff0000, v194
	v_lshlrev_b32_e32 v216, 16, v195
	v_and_b32_e32 v217, 0xffff0000, v195
	v_lshlrev_b32_e32 v218, 16, v196
	v_and_b32_e32 v219, 0xffff0000, v196
	v_lshlrev_b32_e32 v220, 16, v197
	v_and_b32_e32 v221, 0xffff0000, v197
	v_pk_add_f32 v[198:199], v[198:199], v[214:215]
	v_pk_fma_f32 v[222:223], v[72:73], v[198:199], v[214:215] neg_lo:[0,0,1] neg_hi:[0,0,1]
	v_cvt_pk_bf16_f32 v226, v222, v223
	v_pk_add_f32 v[200:201], v[200:201], v[216:217]
	v_pk_fma_f32 v[222:223], v[72:73], v[200:201], v[216:217] neg_lo:[0,0,1] neg_hi:[0,0,1]
	v_cvt_pk_bf16_f32 v227, v222, v223
	v_pk_add_f32 v[202:203], v[202:203], v[218:219]
	v_pk_fma_f32 v[222:223], v[72:73], v[202:203], v[218:219] neg_lo:[0,0,1] neg_hi:[0,0,1]
	v_cvt_pk_bf16_f32 v228, v222, v223
	v_pk_add_f32 v[204:205], v[204:205], v[220:221]
	v_pk_fma_f32 v[222:223], v[72:73], v[204:205], v[220:221] neg_lo:[0,0,1] neg_hi:[0,0,1]
	v_cvt_pk_bf16_f32 v229, v222, v223
	s_add_u32 s70, s70, 0x800
	s_addc_u32 s71, s71, 0
	global_store_dwordx4 v82, v[226:229], s[70:71]
	s_add_u32 s68, s66, 0xe000
	s_addc_u32 s69, s67, 0
	global_store_dwordx4 v185, v[214:217], s[68:69]
	global_store_dwordx4 v185, v[218:221], s[68:69] offset:16
	s_add_u32 s68, s66, 0x0
	s_addc_u32 s69, s67, 0
	global_store_dwordx4 v185, v[150:153], s[68:69]
	global_store_dwordx4 v185, v[156:159], s[68:69] offset:16
	s_add_u32 s68, s68, 0x1000
	s_addc_u32 s69, s69, 0
	global_store_dwordx4 v185, v[142:145], s[68:69]
	global_store_dwordx4 v185, v[146:149], s[68:69] offset:16
	s_add_u32 s68, s68, 0x1000
	s_addc_u32 s69, s69, 0
	global_store_dwordx4 v185, v[134:137], s[68:69]
	global_store_dwordx4 v185, v[138:141], s[68:69] offset:16
	s_add_u32 s68, s68, 0x1000
	s_addc_u32 s69, s69, 0
	global_store_dwordx4 v185, v[60:63], s[68:69]
	global_store_dwordx4 v185, v[130:133], s[68:69] offset:16
	s_add_u32 s68, s68, 0x1000
	s_addc_u32 s69, s69, 0
	global_store_dwordx4 v185, v[52:55], s[68:69]
	global_store_dwordx4 v185, v[56:59], s[68:69] offset:16
	s_add_u32 s68, s68, 0x1000
	s_addc_u32 s69, s69, 0
	global_store_dwordx4 v185, v[44:47], s[68:69]
	global_store_dwordx4 v185, v[48:51], s[68:69] offset:16
	s_add_u32 s68, s68, 0x1000
	s_addc_u32 s69, s69, 0
	global_store_dwordx4 v185, v[36:39], s[68:69]
	global_store_dwordx4 v185, v[40:43], s[68:69] offset:16
	s_add_u32 s68, s68, 0x1000
	s_addc_u32 s69, s69, 0
	global_store_dwordx4 v185, v[28:31], s[68:69]
	global_store_dwordx4 v185, v[32:35], s[68:69] offset:16
	s_add_u32 s68, s68, 0x1000
	s_addc_u32 s69, s69, 0
	global_store_dwordx4 v185, v[20:23], s[68:69]
	global_store_dwordx4 v185, v[24:27], s[68:69] offset:16
	s_add_u32 s68, s68, 0x1000
	s_addc_u32 s69, s69, 0
	global_store_dwordx4 v185, v[12:15], s[68:69]
	global_store_dwordx4 v185, v[16:19], s[68:69] offset:16
	s_add_u32 s68, s68, 0x1000
	s_addc_u32 s69, s69, 0
	global_store_dwordx4 v185, v[8:11], s[68:69]
	s_mul_i32 s68, s64, 15
	s_add_i32 s68, s68, 10
	s_mov_b32 s69, 0
	s_lshl_b64 s[68:69], s[68:69], 12
	v_mov_b32_e32 v27, v6
	v_lshl_add_u64 v[0:1], v[116:117], 0, s[68:69]
	s_branch .Lps_done
.Lps_w7:
	s_load_dwordx2 s[74:75], s[0:1], 0x30
	s_mov_b32 s72, 0
	s_mov_b32 s73, -1
	s_mov_b64 s[76:77], exec
	s_andn2_b64 s[78:79], exec, s[72:73]
	v_lshlrev_b32_e32 v185, 1, v82
	s_mul_i32 s66, s64, 15
	s_mov_b32 s67, 0
	s_lshl_b64 s[66:67], s[66:67], 12
	s_waitcnt lgkmcnt(0)
	s_add_u32 s74, s74, s66
	s_addc_u32 s75, s75, s67
	s_add_u32 s66, s66, s24
	s_addc_u32 s67, s67, s25
	s_add_u32 s66, s66, 0x8ae0000
	s_addc_u32 s67, s67, 0
	s_add_u32 s68, s74, 0xe000
	s_addc_u32 s69, s75, 0
	global_load_dwordx4 v[8:11], v185, s[68:69]
	global_load_dwordx4 v[4:7], v185, s[68:69] offset:16
	s_sub_u32 s68, s68, 0x1000
	s_subb_u32 s69, s69, 0
	global_load_dwordx4 v[12:15], v185, s[68:69]
	global_load_dwordx4 v[16:19], v185, s[68:69] offset:16
	s_sub_u32 s68, s68, 0x1000
	s_subb_u32 s69, s69, 0
	global_load_dwordx4 v[20:23], v185, s[68:69]
	global_load_dwordx4 v[24:27], v185, s[68:69] offset:16
	s_sub_u32 s68, s68, 0x1000
	s_subb_u32 s69, s69, 0
	global_load_dwordx4 v[28:31], v185, s[68:69]
	global_load_dwordx4 v[32:35], v185, s[68:69] offset:16
	s_sub_u32 s68, s68, 0x1000
	s_subb_u32 s69, s69, 0
	global_load_dwordx4 v[36:39], v185, s[68:69]
	global_load_dwordx4 v[40:43], v185, s[68:69] offset:16
	s_sub_u32 s68, s68, 0x1000
	s_subb_u32 s69, s69, 0
	global_load_dwordx4 v[44:47], v185, s[68:69]
	global_load_dwordx4 v[48:51], v185, s[68:69] offset:16
	s_sub_u32 s68, s68, 0x1000
	s_subb_u32 s69, s69, 0
	global_load_dwordx4 v[52:55], v185, s[68:69]
	global_load_dwordx4 v[56:59], v185, s[68:69] offset:16
	s_mul_i32 s70, s65, 0x4a00
	s_mul_hi_u32 s71, s65, 0x4a00
	s_add_u32 s70, s70, s30
	s_addc_u32 s71, s71, s31
	s_add_u32 s70, s70, 0x2000
	s_addc_u32 s71, s71, 0
	global_load_dwordx4 v[60:63], v82, s[70:71]
	s_add_u32 s70, s70, 0x4a00
	s_addc_u32 s71, s71, 0
	global_load_dwordx4 v[130:133], v82, s[70:71]
	s_add_u32 s70, s70, 0x4a00
	s_addc_u32 s71, s71, 0
	global_load_dwordx4 v[134:137], v82, s[70:71]
	s_add_u32 s70, s70, 0x4a00
	s_addc_u32 s71, s71, 0
	global_load_dwordx4 v[138:141], v82, s[70:71]
	s_lshl_b32 s70, s65, 11
	s_add_u32 s70, s70, s26
	s_addc_u32 s71, s27, 0
	s_add_u32 s70, s70, 0xd439000
	s_addc_u32 s71, s71, 0
	s_waitcnt vmcnt(16)
	v_pk_add_f32 v[142:143], v[8:9], 0 op_sel_hi:[1,0]
	v_pk_add_f32 v[144:145], v[10:11], 0 op_sel_hi:[1,0]
	v_pk_add_f32 v[146:147], v[4:5], 0 op_sel_hi:[1,0]
	v_pk_add_f32 v[148:149], v[6:7], 0 op_sel_hi:[1,0]
	s_waitcnt vmcnt(14)
	v_pk_add_f32 v[142:143], v[142:143], v[12:13]
	v_pk_add_f32 v[144:145], v[144:145], v[14:15]
	v_pk_add_f32 v[146:147], v[146:147], v[16:17]
	v_pk_add_f32 v[148:149], v[148:149], v[18:19]
	s_waitcnt vmcnt(12)
; __device__ __forceinline__ u32x4 pack8(const float* f) { u32x4 w; w.x = pk2(f[0], f[1]); w.y = pk2(f[2], f[3]); w.z = pk2(f[4], f[5]); w.w = pk2(f[6], f[7]); return w; }
; template <int NTOK, bool SMP>
; __device__ __forceinline__ void mixer_item(const Params& p, int it) {
;     ...
;         float s[8];
; #pragma unroll
;         for (int i = 0; i < 8; ++i) s[i] = 0.f;
; #pragma unroll
;         for (int q = 1; q < 16; ++q) if (q < w) { float f[8]; xpool(t0 - q, f);
; #pragma unroll
;             for (int i = 0; i < 8; ++i) s[i] += f[i]; }
; #pragma unroll 4
;         for (int t = 0; t < NTOK; ++t) {
;             const int tt = t0 + t; float x[8], y[8], f[8];
;             xpool(tt, x);
;             const float cnt = SMP ? (float)w : (float)min(w, tt + 1); const float ic = 1.0f / cnt;
; #pragma unroll
;             for (int i = 0; i < 8; ++i) { s[i] += x[i]; y[i] = s[i] * ic - x[i]; }
;             *(u32x4*)(yp + (size_t)(seqrow0 + tt) * 1024 + pc) = pack8(y);
;             xpool(tt - w + 1, f);
; #pragma unroll
;             for (int i = 0; i < 8; ++i) s[i] -= f[i];
;             if (SMP) { float* o = p.out + O_PS + ((size_t)sb * 15 + 11 + t) * 1024 + pc; *(f32x4*)o = (f32x4){x[0], x[1], x[2], x[3]}; *(f32x4*)(o + 4) = (f32x4){x[4], x[5], x[6], x[7]}; }
;             else if (tt >= 2033) { float* o = p.out + O_PP + ((size_t)b * 15 + (tt - 2033)) * 1024 + pc; *(f32x4*)o = (f32x4){x[0], x[1], x[2], x[3]}; *(f32x4*)(o + 4) = (f32x4){x[4], x[5], x[6], x[7]}; }
;         }
;         if (SMP) {
; #pragma unroll
;             for (int r = 0; r < 11; ++r) { const float* s2 = sp + (size_t)(4 + r) * 1024; float* o = p.out + O_PS + ((size_t)sb * 15 + r) * 1024 + pc; *(f32x4*)o = *(const f32x4*)s2; *(f32x4*)(o + 4) = *(const f32x4*)(s2 + 4); } }
	v_pk_add_f32 v[142:143], v[142:143], v[20:21]
	v_pk_add_f32 v[144:145], v[144:145], v[22:23]
	v_pk_add_f32 v[146:147], v[146:147], v[24:25]
	v_pk_add_f32 v[148:149], v[148:149], v[26:27]
	s_waitcnt vmcnt(10)
	v_pk_add_f32 v[142:143], v[142:143], v[28:29]
	v_pk_add_f32 v[144:145], v[144:145], v[30:31]
	v_pk_add_f32 v[146:147], v[146:147], v[32:33]
	v_pk_add_f32 v[148:149], v[148:149], v[34:35]
	s_waitcnt vmcnt(8)
	v_pk_add_f32 v[142:143], v[142:143], v[36:37]
	v_pk_add_f32 v[144:145], v[144:145], v[38:39]
	v_pk_add_f32 v[146:147], v[146:147], v[40:41]
	v_pk_add_f32 v[148:149], v[148:149], v[42:43]
	s_waitcnt vmcnt(6)
	v_pk_add_f32 v[142:143], v[142:143], v[44:45]
	v_pk_add_f32 v[144:145], v[144:145], v[46:47]
	v_pk_add_f32 v[146:147], v[146:147], v[48:49]
	v_pk_add_f32 v[148:149], v[148:149], v[50:51]
	s_waitcnt vmcnt(4)
	v_pk_add_f32 v[142:143], v[142:143], v[52:53]
	v_pk_add_f32 v[144:145], v[144:145], v[54:55]
	v_pk_add_f32 v[146:147], v[146:147], v[56:57]
	v_pk_add_f32 v[148:149], v[148:149], v[58:59]
	s_add_u32 s68, s66, 0x4000
	s_addc_u32 s69, s67, 0
	global_store_dwordx4 v185, v[52:55], s[68:69]
	global_store_dwordx4 v185, v[56:59], s[68:69] offset:16
	s_add_u32 s68, s68, 0x1000
	s_addc_u32 s69, s69, 0
	global_store_dwordx4 v185, v[44:47], s[68:69]
	global_store_dwordx4 v185, v[48:51], s[68:69] offset:16
	s_add_u32 s68, s68, 0x1000
	s_addc_u32 s69, s69, 0
	global_store_dwordx4 v185, v[36:39], s[68:69]
	global_store_dwordx4 v185, v[40:43], s[68:69] offset:16
	s_add_u32 s68, s68, 0x1000
	s_addc_u32 s69, s69, 0
	global_store_dwordx4 v185, v[28:31], s[68:69]
	global_store_dwordx4 v185, v[32:35], s[68:69] offset:16
	s_add_u32 s68, s68, 0x1000
	s_addc_u32 s69, s69, 0
	global_store_dwordx4 v185, v[20:23], s[68:69]
	global_store_dwordx4 v185, v[24:27], s[68:69] offset:16
	s_add_u32 s68, s68, 0x1000
	s_addc_u32 s69, s69, 0
	global_store_dwordx4 v185, v[12:15], s[68:69]
	global_store_dwordx4 v185, v[16:19], s[68:69] offset:16
	s_add_u32 s68, s68, 0x1000
	s_addc_u32 s69, s69, 0
	global_store_dwordx4 v185, v[8:11], s[68:69]
	s_nop 1
	s_add_u32 s68, s74, 0x7000
	s_addc_u32 s69, s75, 0
	global_load_dwordx4 v[8:11], v185, s[68:69]
	global_load_dwordx4 v[12:15], v185, s[68:69] offset:16
	s_sub_u32 s68, s68, 0x1000
	s_subb_u32 s69, s69, 0
	global_load_dwordx4 v[16:19], v185, s[68:69]
	global_load_dwordx4 v[20:23], v185, s[68:69] offset:16
	s_sub_u32 s68, s68, 0x1000
	s_subb_u32 s69, s69, 0
	global_load_dwordx4 v[24:27], v185, s[68:69]
	global_load_dwordx4 v[28:31], v185, s[68:69] offset:16
	s_sub_u32 s68, s68, 0x1000
	s_subb_u32 s69, s69, 0
	global_load_dwordx4 v[32:35], v185, s[68:69]
	global_load_dwordx4 v[150:153], v185, s[68:69] offset:16
	s_sub_u32 s68, s68, 0x1000
	s_subb_u32 s69, s69, 0
	global_load_dwordx4 v[156:159], v185, s[68:69]
	global_load_dwordx4 v[162:165], v185, s[68:69] offset:16
	s_sub_u32 s68, s68, 0x1000
	s_subb_u32 s69, s69, 0
	global_load_dwordx4 v[186:189], v185, s[68:69]
	global_load_dwordx4 v[190:193], v185, s[68:69] offset:16
	s_sub_u32 s68, s68, 0x1000
	s_subb_u32 s69, s69, 0
	global_load_dwordx4 v[194:197], v185, s[68:69]
	global_load_dwordx4 v[198:201], v185, s[68:69] offset:16
	s_sub_u32 s68, s68, 0x1000
	s_subb_u32 s69, s69, 0
	global_load_dwordx4 v[202:205], v185, s[68:69]
	global_load_dwordx4 v[206:209], v185, s[68:69] offset:16
	s_mov_b64 exec, s[72:73]
	s_waitcnt vmcnt(14)
	v_pk_add_f32 v[142:143], v[142:143], v[8:9]
	v_pk_add_f32 v[144:145], v[144:145], v[10:11]
	v_pk_add_f32 v[146:147], v[146:147], v[12:13]
	v_pk_add_f32 v[148:149], v[148:149], v[14:15]
	s_waitcnt vmcnt(12)
	v_pk_add_f32 v[142:143], v[142:143], v[16:17]
	v_pk_add_f32 v[144:145], v[144:145], v[18:19]
	v_pk_add_f32 v[146:147], v[146:147], v[20:21]
	v_pk_add_f32 v[148:149], v[148:149], v[22:23]
	s_waitcnt vmcnt(10)
	v_pk_add_f32 v[142:143], v[142:143], v[24:25]
	v_pk_add_f32 v[144:145], v[144:145], v[26:27]
	v_pk_add_f32 v[146:147], v[146:147], v[28:29]
	v_pk_add_f32 v[148:149], v[148:149], v[30:31]
	s_waitcnt vmcnt(8)
	v_pk_add_f32 v[142:143], v[142:143], v[32:33]
	v_pk_add_f32 v[144:145], v[144:145], v[34:35]
	v_pk_add_f32 v[146:147], v[146:147], v[150:151]
	v_pk_add_f32 v[148:149], v[148:149], v[152:153]
	s_waitcnt vmcnt(6)
	v_pk_add_f32 v[142:143], v[142:143], v[156:157]
	v_pk_add_f32 v[144:145], v[144:145], v[158:159]
	v_pk_add_f32 v[146:147], v[146:147], v[162:163]
	v_pk_add_f32 v[148:149], v[148:149], v[164:165]
	s_waitcnt vmcnt(4)
	v_pk_add_f32 v[142:143], v[142:143], v[186:187]
	v_pk_add_f32 v[144:145], v[144:145], v[188:189]
	v_pk_add_f32 v[146:147], v[146:147], v[190:191]
	v_pk_add_f32 v[148:149], v[148:149], v[192:193]
	s_waitcnt vmcnt(2)
	v_pk_add_f32 v[142:143], v[142:143], v[194:195]
	v_pk_add_f32 v[144:145], v[144:145], v[196:197]
	v_pk_add_f32 v[146:147], v[146:147], v[198:199]
	v_pk_add_f32 v[148:149], v[148:149], v[200:201]
	s_waitcnt vmcnt(0)
	v_pk_add_f32 v[142:143], v[142:143], v[202:203]
	v_pk_add_f32 v[144:145], v[144:145], v[204:205]
	v_pk_add_f32 v[146:147], v[146:147], v[206:207]
	v_pk_add_f32 v[148:149], v[148:149], v[208:209]
	s_mov_b64 exec, s[76:77]
	s_add_u32 s68, s66, 0x0
	s_addc_u32 s69, s67, 0
	global_store_dwordx4 v185, v[32:35], s[68:69]
	global_store_dwordx4 v185, v[150:153], s[68:69] offset:16
	s_add_u32 s68, s68, 0x1000
	s_addc_u32 s69, s69, 0
	global_store_dwordx4 v185, v[24:27], s[68:69]
	global_store_dwordx4 v185, v[28:31], s[68:69] offset:16
	s_add_u32 s68, s68, 0x1000
	s_addc_u32 s69, s69, 0
	global_store_dwordx4 v185, v[16:19], s[68:69]
	global_store_dwordx4 v185, v[20:23], s[68:69] offset:16
	s_add_u32 s68, s68, 0x1000
	s_addc_u32 s69, s69, 0
	global_store_dwordx4 v185, v[8:11], s[68:69]
	global_store_dwordx4 v185, v[12:15], s[68:69] offset:16
	s_waitcnt vmcnt(40)
; __device__ __forceinline__ u32x4 pack8(const float* f) { u32x4 w; w.x = pk2(f[0], f[1]); w.y = pk2(f[2], f[3]); w.z = pk2(f[4], f[5]); w.w = pk2(f[6], f[7]); return w; }
; template <int NTOK, bool SMP>
; __device__ __forceinline__ void mixer_item(const Params& p, int it) {
;     ...
;         for (int t = 0; t < NTOK; ++t) {
;             const int tt = t0 + t; float x[8], y[8], f[8];
;             xpool(tt, x);
;             const float cnt = SMP ? (float)w : (float)min(w, tt + 1); const float ic = 1.0f / cnt;
; #pragma unroll
;             for (int i = 0; i < 8; ++i) { s[i] += x[i]; y[i] = s[i] * ic - x[i]; }
;             *(u32x4*)(yp + (size_t)(seqrow0 + tt) * 1024 + pc) = pack8(y);
;             xpool(tt - w + 1, f);
; #pragma unroll
;             for (int i = 0; i < 8; ++i) s[i] -= f[i];
;             if (SMP) { float* o = p.out + O_PS + ((size_t)sb * 15 + 11 + t) * 1024 + pc; *(f32x4*)o = (f32x4){x[0], x[1], x[2], x[3]}; *(f32x4*)(o + 4) = (f32x4){x[4], x[5], x[6], x[7]}; }
;             else if (tt >= 2033) { float* o = p.out + O_PP + ((size_t)b * 15 + (tt - 2033)) * 1024 + pc; *(f32x4*)o = (f32x4){x[0], x[1], x[2], x[3]}; *(f32x4*)(o + 4) = (f32x4){x[4], x[5], x[6], x[7]}; }
	v_lshlrev_b32_e32 v210, 16, v60
	v_and_b32_e32 v211, 0xffff0000, v60
	v_lshlrev_b32_e32 v212, 16, v61
	v_and_b32_e32 v213, 0xffff0000, v61
	v_lshlrev_b32_e32 v214, 16, v62
	v_and_b32_e32 v215, 0xffff0000, v62
	v_lshlrev_b32_e32 v216, 16, v63
	v_and_b32_e32 v217, 0xffff0000, v63
	v_pk_add_f32 v[142:143], v[142:143], v[210:211]
	v_pk_fma_f32 v[226:227], v[72:73], v[142:143], v[210:211] neg_lo:[0,0,1] neg_hi:[0,0,1]
	v_cvt_pk_bf16_f32 v0, v226, v227
	v_pk_add_f32 v[144:145], v[144:145], v[212:213]
	v_pk_fma_f32 v[226:227], v[72:73], v[144:145], v[212:213] neg_lo:[0,0,1] neg_hi:[0,0,1]
	v_cvt_pk_bf16_f32 v1, v226, v227
	v_pk_add_f32 v[146:147], v[146:147], v[214:215]
	v_pk_fma_f32 v[226:227], v[72:73], v[146:147], v[214:215] neg_lo:[0,0,1] neg_hi:[0,0,1]
	v_cvt_pk_bf16_f32 v2, v226, v227
	v_pk_add_f32 v[148:149], v[148:149], v[216:217]
	v_pk_fma_f32 v[226:227], v[72:73], v[148:149], v[216:217] neg_lo:[0,0,1] neg_hi:[0,0,1]
	v_cvt_pk_bf16_f32 v3, v226, v227
	global_store_dwordx4 v82, v[0:3], s[70:71]
	s_add_u32 s68, s66, 0xb000
	s_addc_u32 s69, s67, 0
	global_store_dwordx4 v185, v[210:213], s[68:69]
	global_store_dwordx4 v185, v[214:217], s[68:69] offset:16
	s_mov_b64 exec, s[78:79]
	v_pk_add_f32 v[142:143], v[142:143], v[52:53] neg_lo:[0,1] neg_hi:[0,1]
	v_pk_add_f32 v[144:145], v[144:145], v[54:55] neg_lo:[0,1] neg_hi:[0,1]
	v_pk_add_f32 v[146:147], v[146:147], v[56:57] neg_lo:[0,1] neg_hi:[0,1]
	v_pk_add_f32 v[148:149], v[148:149], v[58:59] neg_lo:[0,1] neg_hi:[0,1]
	s_mov_b64 exec, s[72:73]
	v_pk_add_f32 v[142:143], v[142:143], v[202:203] neg_lo:[0,1] neg_hi:[0,1]
	v_pk_add_f32 v[144:145], v[144:145], v[204:205] neg_lo:[0,1] neg_hi:[0,1]
	v_pk_add_f32 v[146:147], v[146:147], v[206:207] neg_lo:[0,1] neg_hi:[0,1]
	v_pk_add_f32 v[148:149], v[148:149], v[208:209] neg_lo:[0,1] neg_hi:[0,1]
	s_mov_b64 exec, s[76:77]
	s_waitcnt vmcnt(42)
	v_lshlrev_b32_e32 v218, 16, v130
	v_and_b32_e32 v219, 0xffff0000, v130
	v_lshlrev_b32_e32 v220, 16, v131
	v_and_b32_e32 v221, 0xffff0000, v131
	v_lshlrev_b32_e32 v222, 16, v132
	v_and_b32_e32 v223, 0xffff0000, v132
	v_lshlrev_b32_e32 v224, 16, v133
	v_and_b32_e32 v225, 0xffff0000, v133
	v_pk_add_f32 v[142:143], v[142:143], v[218:219]
	v_pk_fma_f32 v[226:227], v[72:73], v[142:143], v[218:219] neg_lo:[0,0,1] neg_hi:[0,0,1]
	v_cvt_pk_bf16_f32 v230, v226, v227
	v_pk_add_f32 v[144:145], v[144:145], v[220:221]
	v_pk_fma_f32 v[226:227], v[72:73], v[144:145], v[220:221] neg_lo:[0,0,1] neg_hi:[0,0,1]
	v_cvt_pk_bf16_f32 v231, v226, v227
	v_pk_add_f32 v[146:147], v[146:147], v[222:223]
	v_pk_fma_f32 v[226:227], v[72:73], v[146:147], v[222:223] neg_lo:[0,0,1] neg_hi:[0,0,1]
	v_cvt_pk_bf16_f32 v232, v226, v227
	v_pk_add_f32 v[148:149], v[148:149], v[224:225]
	v_pk_fma_f32 v[226:227], v[72:73], v[148:149], v[224:225] neg_lo:[0,0,1] neg_hi:[0,0,1]
	v_cvt_pk_bf16_f32 v233, v226, v227
	s_add_u32 s70, s70, 0x800
	s_addc_u32 s71, s71, 0
	global_store_dwordx4 v82, v[230:233], s[70:71]
	s_add_u32 s68, s66, 0xc000
	s_addc_u32 s69, s67, 0
	global_store_dwordx4 v185, v[218:221], s[68:69]
	global_store_dwordx4 v185, v[222:225], s[68:69] offset:16
	s_mov_b64 exec, s[78:79]
	v_pk_add_f32 v[142:143], v[142:143], v[44:45] neg_lo:[0,1] neg_hi:[0,1]
	v_pk_add_f32 v[144:145], v[144:145], v[46:47] neg_lo:[0,1] neg_hi:[0,1]
	v_pk_add_f32 v[146:147], v[146:147], v[48:49] neg_lo:[0,1] neg_hi:[0,1]
	v_pk_add_f32 v[148:149], v[148:149], v[50:51] neg_lo:[0,1] neg_hi:[0,1]
	s_mov_b64 exec, s[72:73]
	v_pk_add_f32 v[142:143], v[142:143], v[194:195] neg_lo:[0,1] neg_hi:[0,1]
	v_pk_add_f32 v[144:145], v[144:145], v[196:197] neg_lo:[0,1] neg_hi:[0,1]
	v_pk_add_f32 v[146:147], v[146:147], v[198:199] neg_lo:[0,1] neg_hi:[0,1]
	v_pk_add_f32 v[148:149], v[148:149], v[200:201] neg_lo:[0,1] neg_hi:[0,1]
	s_mov_b64 exec, s[76:77]
	s_waitcnt vmcnt(44)
; __device__ __forceinline__ u32x4 pack8(const float* f) { u32x4 w; w.x = pk2(f[0], f[1]); w.y = pk2(f[2], f[3]); w.z = pk2(f[4], f[5]); w.w = pk2(f[6], f[7]); return w; }
; template <int NTOK, bool SMP>
; __device__ __forceinline__ void mixer_item(const Params& p, int it) {
;     ...
;         for (int t = 0; t < NTOK; ++t) {
;             const int tt = t0 + t; float x[8], y[8], f[8];
;             xpool(tt, x);
;             const float cnt = SMP ? (float)w : (float)min(w, tt + 1); const float ic = 1.0f / cnt;
; #pragma unroll
;             for (int i = 0; i < 8; ++i) { s[i] += x[i]; y[i] = s[i] * ic - x[i]; }
;             *(u32x4*)(yp + (size_t)(seqrow0 + tt) * 1024 + pc) = pack8(y);
;             xpool(tt - w + 1, f);
; #pragma unroll
;             for (int i = 0; i < 8; ++i) s[i] -= f[i];
;             if (SMP) { float* o = p.out + O_PS + ((size_t)sb * 15 + 11 + t) * 1024 + pc; *(f32x4*)o = (f32x4){x[0], x[1], x[2], x[3]}; *(f32x4*)(o + 4) = (f32x4){x[4], x[5], x[6], x[7]}; }
;             else if (tt >= 2033) { float* o = p.out + O_PP + ((size_t)b * 15 + (tt - 2033)) * 1024 + pc; *(f32x4*)o = (f32x4){x[0], x[1], x[2], x[3]}; *(f32x4*)(o + 4) = (f32x4){x[4], x[5], x[6], x[7]}; }
	v_lshlrev_b32_e32 v210, 16, v134
	v_and_b32_e32 v211, 0xffff0000, v134
	v_lshlrev_b32_e32 v212, 16, v135
	v_and_b32_e32 v213, 0xffff0000, v135
	v_lshlrev_b32_e32 v214, 16, v136
	v_and_b32_e32 v215, 0xffff0000, v136
	v_lshlrev_b32_e32 v216, 16, v137
	v_and_b32_e32 v217, 0xffff0000, v137
	v_pk_add_f32 v[142:143], v[142:143], v[210:211]
	v_pk_fma_f32 v[226:227], v[72:73], v[142:143], v[210:211] neg_lo:[0,0,1] neg_hi:[0,0,1]
	v_cvt_pk_bf16_f32 v0, v226, v227
	v_pk_add_f32 v[144:145], v[144:145], v[212:213]
	v_pk_fma_f32 v[226:227], v[72:73], v[144:145], v[212:213] neg_lo:[0,0,1] neg_hi:[0,0,1]
	v_cvt_pk_bf16_f32 v1, v226, v227
	v_pk_add_f32 v[146:147], v[146:147], v[214:215]
	v_pk_fma_f32 v[226:227], v[72:73], v[146:147], v[214:215] neg_lo:[0,0,1] neg_hi:[0,0,1]
	v_cvt_pk_bf16_f32 v2, v226, v227
	v_pk_add_f32 v[148:149], v[148:149], v[216:217]
	v_pk_fma_f32 v[226:227], v[72:73], v[148:149], v[216:217] neg_lo:[0,0,1] neg_hi:[0,0,1]
	v_cvt_pk_bf16_f32 v3, v226, v227
	s_add_u32 s70, s70, 0x800
	s_addc_u32 s71, s71, 0
	global_store_dwordx4 v82, v[0:3], s[70:71]
	s_add_u32 s68, s66, 0xd000
	s_addc_u32 s69, s67, 0
	global_store_dwordx4 v185, v[210:213], s[68:69]
	global_store_dwordx4 v185, v[214:217], s[68:69] offset:16
	s_mov_b64 exec, s[78:79]
	v_pk_add_f32 v[142:143], v[142:143], v[36:37] neg_lo:[0,1] neg_hi:[0,1]
	v_pk_add_f32 v[144:145], v[144:145], v[38:39] neg_lo:[0,1] neg_hi:[0,1]
	v_pk_add_f32 v[146:147], v[146:147], v[40:41] neg_lo:[0,1] neg_hi:[0,1]
	v_pk_add_f32 v[148:149], v[148:149], v[42:43] neg_lo:[0,1] neg_hi:[0,1]
	s_mov_b64 exec, s[72:73]
	v_pk_add_f32 v[142:143], v[142:143], v[186:187] neg_lo:[0,1] neg_hi:[0,1]
	v_pk_add_f32 v[144:145], v[144:145], v[188:189] neg_lo:[0,1] neg_hi:[0,1]
	v_pk_add_f32 v[146:147], v[146:147], v[190:191] neg_lo:[0,1] neg_hi:[0,1]
	v_pk_add_f32 v[148:149], v[148:149], v[192:193] neg_lo:[0,1] neg_hi:[0,1]
	s_mov_b64 exec, s[76:77]
	s_waitcnt vmcnt(46)
	v_lshlrev_b32_e32 v218, 16, v138
	v_and_b32_e32 v219, 0xffff0000, v138
	v_lshlrev_b32_e32 v220, 16, v139
	v_and_b32_e32 v221, 0xffff0000, v139
	v_lshlrev_b32_e32 v222, 16, v140
	v_and_b32_e32 v223, 0xffff0000, v140
	v_lshlrev_b32_e32 v224, 16, v141
	v_and_b32_e32 v225, 0xffff0000, v141
	v_pk_add_f32 v[142:143], v[142:143], v[218:219]
	v_pk_fma_f32 v[226:227], v[72:73], v[142:143], v[218:219] neg_lo:[0,0,1] neg_hi:[0,0,1]
	v_cvt_pk_bf16_f32 v230, v226, v227
	v_pk_add_f32 v[144:145], v[144:145], v[220:221]
	v_pk_fma_f32 v[226:227], v[72:73], v[144:145], v[220:221] neg_lo:[0,0,1] neg_hi:[0,0,1]
	v_cvt_pk_bf16_f32 v231, v226, v227
	v_pk_add_f32 v[146:147], v[146:147], v[222:223]
	v_pk_fma_f32 v[226:227], v[72:73], v[146:147], v[222:223] neg_lo:[0,0,1] neg_hi:[0,0,1]
	v_cvt_pk_bf16_f32 v232, v226, v227
	v_pk_add_f32 v[148:149], v[148:149], v[224:225]
	v_pk_fma_f32 v[226:227], v[72:73], v[148:149], v[224:225] neg_lo:[0,0,1] neg_hi:[0,0,1]
	v_cvt_pk_bf16_f32 v233, v226, v227
	s_add_u32 s70, s70, 0x800
	s_addc_u32 s71, s71, 0
	global_store_dwordx4 v82, v[230:233], s[70:71]
	s_add_u32 s68, s66, 0xe000
	s_addc_u32 s69, s67, 0
	global_store_dwordx4 v185, v[218:221], s[68:69]
	global_store_dwordx4 v185, v[222:225], s[68:69] offset:16
	s_mul_i32 s68, s64, 15
	s_add_i32 s68, s68, 10
	s_mov_b32 s69, 0
	s_lshl_b64 s[68:69], s[68:69], 12
	v_mov_b32_e32 v27, v6
	v_lshl_add_u64 v[0:1], v[116:117], 0, s[68:69]
.Lps_done:
	s_branch .Lps_join
.LBB0_833:
	s_andn2_saveexec_b64 s[22:23], s[60:61]
	s_cbranch_execnz .LBB0_857
	s_branch .LBB0_898
.Lps_join:
	s_andn2_saveexec_b64 s[22:23], s[60:61]
	s_cbranch_execz .LBB0_898

; #define LAS __attribute__((address_space(3)))
; __device__ __forceinline__ void chunk_prep_phase(const Params& p, int bid, int nblk, LAS unsigned char* lds0) {
;     ...
;     for (int it0 = bid * 2; it0 < 1024; it0 += nblk * 2) {
;         const int item = it0 + grp, n = item & 31, bh = item >> 5, h = bh & 7, b = bh >> 3;
;         const int r0 = b * 2048 + n * 64;
;         __syncthreads();
; #pragma unroll
;         for (int i = 0; i < 4; ++i) { const int ch = lt + 256 * i, r = ch >> 4, c8 = (ch & 15) * 8; const size_t go = (size_t)(r0 + r) * 1024 + h * 128 + c8; const int lo = r * 272 + c8 * 2;
;             *(LAS u32x4*)(lds + P5_QS + lo) = *(const u32x4*)(qn + go); *(LAS u32x4*)(lds + P5_KS + lo) = *(const u32x4*)(kn + go); *(LAS u32x4*)(lds + P5_VS + lo) = *(const u32x4*)(vv + go); }
;         if (lt < 64) {
;             float g = gbuf[(r0 + lt) * 8 + h];
; #pragma unroll
;             for (int o = 1; o < 64; o <<= 1) { const float t = __shfl_up(g, o); if (lane >= o) g += t; }
;             dec[lt] = g;
;         } else if (lt < 128) bet[lt - 64] = bbuf[(r0 + lt - 64) * 8 + h];
.LBB0_963:
	v_and_b32_e32 v1, 0x7c0, v180
	s_movk_i32 s7, 0xf800
	v_and_or_b32 v1, v179, s7, v1
	v_add_u32_e32 v0, s97, v150
	v_or_b32_e32 v2, v1, v153
	v_bfe_u32 v0, v0, 5, 3
	v_ashrrev_i32_e32 v3, 31, v2
	v_lshlrev_b64 v[6:7], 11, v[2:3]
	v_lshl_or_b32 v8, v0, 8, v52
	v_or_b32_e32 v6, v6, v8
	v_lshl_add_u64 v[2:3], s[94:95], 0, v[6:7]
	s_barrier
	global_load_dwordx4 v[84:87], v[2:3], off
	v_lshl_add_u64 v[2:3], s[4:5], 0, v[6:7]
	global_load_dwordx4 v[88:91], v[2:3], off
	v_lshl_add_u64 v[2:3], s[92:93], 0, v[6:7]
	global_load_dwordx4 v[92:95], v[2:3], off
	v_or_b32_e32 v2, v1, v154
	v_ashrrev_i32_e32 v3, 31, v2
	v_lshlrev_b64 v[6:7], 11, v[2:3]
	v_or_b32_e32 v6, v6, v8
	v_lshl_add_u64 v[2:3], s[94:95], 0, v[6:7]
	global_load_dwordx4 v[96:99], v[2:3], off
	v_lshl_add_u64 v[2:3], s[4:5], 0, v[6:7]
	global_load_dwordx4 v[100:103], v[2:3], off
	v_lshl_add_u64 v[2:3], s[92:93], 0, v[6:7]
	global_load_dwordx4 v[104:107], v[2:3], off
	v_or_b32_e32 v2, v1, v155
	v_ashrrev_i32_e32 v3, 31, v2
	v_lshlrev_b64 v[6:7], 11, v[2:3]
	v_or_b32_e32 v6, v6, v8
	v_lshl_add_u64 v[2:3], s[94:95], 0, v[6:7]
	global_load_dwordx4 v[108:111], v[2:3], off
	v_lshl_add_u64 v[2:3], s[4:5], 0, v[6:7]
	global_load_dwordx4 v[112:115], v[2:3], off
	v_lshl_add_u64 v[2:3], s[92:93], 0, v[6:7]
	global_load_dwordx4 v[116:119], v[2:3], off
	v_or_b32_e32 v2, v1, v156
	v_ashrrev_i32_e32 v3, 31, v2
	v_lshlrev_b64 v[6:7], 11, v[2:3]
	v_or_b32_e32 v6, v6, v8
	v_lshl_add_u64 v[2:3], s[94:95], 0, v[6:7]
	global_load_dwordx4 v[120:123], v[2:3], off
	v_lshl_add_u64 v[2:3], s[4:5], 0, v[6:7]
	global_load_dwordx4 v[124:127], v[2:3], off
	v_lshl_add_u64 v[2:3], s[92:93], 0, v[6:7]
	global_load_dwordx4 v[128:131], v[2:3], off
	s_waitcnt vmcnt(11)
	ds_write_b128 v181, v[84:87]
	s_waitcnt vmcnt(10)
	ds_write_b128 v181, v[88:91] offset:17408
	s_waitcnt vmcnt(9)
	ds_write_b128 v181, v[92:95] offset:34816
	s_waitcnt vmcnt(8)
	ds_write_b128 v181, v[96:99] offset:4352
	s_waitcnt vmcnt(7)
	ds_write_b128 v181, v[100:103] offset:21760
	s_waitcnt vmcnt(6)
	ds_write_b128 v181, v[104:107] offset:39168
	s_waitcnt vmcnt(5)
	ds_write_b128 v181, v[108:111] offset:8704
	s_waitcnt vmcnt(4)
	ds_write_b128 v181, v[112:115] offset:26112
	s_waitcnt vmcnt(3)
	ds_write_b128 v181, v[116:119] offset:43520
	s_waitcnt vmcnt(2)
	ds_write_b128 v182, v[120:123]
	s_waitcnt vmcnt(1)
	ds_write_b128 v182, v[124:127] offset:17408
	s_waitcnt vmcnt(0)
	ds_write_b128 v182, v[128:131] offset:34816
	s_and_saveexec_b64 s[8:9], s[88:89]
	s_xor_b64 s[8:9], exec, s[8:9]
	s_cbranch_execz .LBB0_967
	s_mov_b64 vcc, exec
	v_readlane_b32 s10, v236, 15
	v_readlane_b32 s11, v236, 16
	s_and_b64 s[10:11], vcc, s[10:11]
	s_mov_b64 exec, s[10:11]
	s_cbranch_execz .LBB0_966
	v_add_u32_sdwa v1, v1, v160 dst_sel:DWORD dst_unused:UNUSED_PAD src0_sel:DWORD src1_sel:BYTE_0
	v_lshl_or_b32 v0, v1, 3, v0
	v_add_u32_e32 v0, 0xfffffe00, v0
	v_readlane_b32 s10, v236, 8
	v_ashrrev_i32_e32 v1, 31, v0
	v_readlane_b32 s11, v236, 9
	s_nop 1
	v_lshl_add_u64 v[0:1], v[0:1], 2, s[10:11]
	global_load_dword v0, v[0:1], off
	s_waitcnt vmcnt(0)
	ds_write_b32 v151, v0

; __device__ __forceinline__ void transpose_jobs(const TJob* jobs, int njobs, int bi, int nblk, LAS unsigned char* lds) {
;     ...
;     f32x4 v[4]; int curj = 0, base = 0;
;     int t = bi;
;     auto locate = [&](int tt, int& jj, int& bb) { while (tt >= bb + (jobs[jj].Nout >> 6) * (jobs[jj].K >> 7)) { bb += (jobs[jj].Nout >> 6) * (jobs[jj].K >> 7); ++jj; } };
;     if (t < total) { locate(t, curj, base); tjob_load(jobs[curj], t - base, v); }
;     while (t < total) {
;         const int tn = t + nblk; int nj = curj, nb = base; f32x4 w[4];
;         if (tn < total) { locate(tn, nj, nb); tjob_load(jobs[nj], tn - nb, w); }
.LBB0_1283:
	s_or_b64 exec, exec, s[6:7]
	s_movk_i32 s21, 0x7f
	s_movk_i32 s22, 0xfff
	s_movk_i32 s23, 0x2410
	v_lshlrev_b32_e32 v0, 1, v150
	s_mov_b32 s25, s2
	s_waitcnt vmcnt(0)
	s_branch .LBB0_1286

; #define LAS __attribute__((address_space(3)))
; __device__ __forceinline__ u32x4 pack8(const float* f) { u32x4 w; w.x = pk2(f[0], f[1]); w.y = pk2(f[2], f[3]); w.z = pk2(f[4], f[5]); w.w = pk2(f[6], f[7]); return w; }
; __device__ __forceinline__ void tjob_store(const TJob& j, int tile, const f32x4 (&v)[4], LAS float* s) {
;     const int tid = threadIdx.x, nkt = j.K >> 7, tn = tile / nkt, tk = tile - tn * nkt;
;     const int nq = tid & 15, kr = tid >> 4;
;     __syncthreads();
; #pragma unroll
;     for (int i = 0; i < 4; ++i)
; #pragma unroll
;         for (int q = 0; q < 4; ++q) s[(4 * nq + q) * 129 + kr + 32 * i] = v[i][q];
;     __syncthreads();
;     const int n = tid >> 3, k16 = (tid & 7) * 16;
;     float f[16];
; #pragma unroll
;     for (int i = 0; i < 16; ++i) f[i] = s[n * 129 + k16 + i];
;     bf16_t* d = j.dst + (size_t)(tn * 64 + n) * j.ld_dst + tk * 128 + k16;
;     *(u32x4*)d = pack8(f); *(u32x4*)(d + 8) = pack8(f + 8);
; }
; __device__ __forceinline__ void transpose_jobs(const TJob* jobs, int njobs, int bi, int nblk, LAS unsigned char* lds) {
;     LAS float* s = (LAS float*)lds;
;     int total = 0;
;     for (int q = 0; q < njobs; ++q) total += (jobs[q].Nout >> 6) * (jobs[q].K >> 7);
;     f32x4 v[4]; int curj = 0, base = 0;
;     int t = bi;
;     auto locate = [&](int tt, int& jj, int& bb) { while (tt >= bb + (jobs[jj].Nout >> 6) * (jobs[jj].K >> 7)) { bb += (jobs[jj].Nout >> 6) * (jobs[jj].K >> 7); ++jj; } };
;     if (t < total) { locate(t, curj, base); tjob_load(jobs[curj], t - base, v); }
;     while (t < total) {
;         const int tn = t + nblk; int nj = curj, nb = base; f32x4 w[4];
;         if (tn < total) { locate(tn, nj, nb); tjob_load(jobs[nj], tn - nb, w); }
;         tjob_store(jobs[curj], t - base, v, s);
;         if (tn < total) {
; #pragma unroll
;             for (int i = 0; i < 4; ++i) v[i] = w[i]; }
;         t = tn; curj = nj; base = nb;
;     }
.LBB0_1285:
	s_mul_i32 s13, s13, 40
	s_mul_hi_u32 s14, s12, 40
	s_add_i32 s14, s14, s13
	s_mul_i32 s12, s12, 40
	s_add_u32 s12, s0, s12
	v_add_u32_e32 v32, v39, v40
	s_addc_u32 s13, s1, s14
	s_barrier
	ds_write2_b32 v32, v33, v4 offset1:32
	ds_write2_b32 v32, v1, v5 offset0:129 offset1:161
	v_add_u32_e32 v1, 0x400, v32
	ds_write2_b32 v1, v2, v6 offset0:2 offset1:34
	ds_write2_b32 v1, v3, v7 offset0:131 offset1:163
	ds_write2_b32 v32, v8, v12 offset0:64 offset1:96
	ds_write2_b32 v32, v9, v13 offset0:193 offset1:225
	ds_write2_b32 v1, v10, v14 offset0:66 offset1:98
	ds_write2_b32 v1, v11, v15 offset0:195 offset1:227
	s_waitcnt lgkmcnt(0)
	s_barrier
	s_load_dword s16, s[12:13], 0x164
	s_load_dwordx2 s[14:15], s[12:13], 0x158
	s_load_dword s18, s[12:13], 0x16c
	s_sub_i32 s17, s25, s20
	s_abs_i32 s19, s17
	ds_read2_b32 v[2:3], v41 offset1:1
	ds_read2_b32 v[4:5], v41 offset0:2 offset1:3
	ds_read2_b32 v[6:7], v41 offset0:4 offset1:5
	ds_read2_b32 v[8:9], v41 offset0:6 offset1:7
	s_waitcnt lgkmcnt(0)
	s_ashr_i32 s12, s16, 7
	s_abs_i32 s13, s12
	v_cvt_f32_u32_e32 v1, s13
	s_sub_i32 s20, 0, s13
	s_xor_b32 s16, s17, s12
	s_ashr_i32 s16, s16, 31
	v_rcp_iflag_f32_e32 v1, v1
	ds_read2_b32 v[10:11], v41 offset0:8 offset1:9
	ds_read2_b32 v[12:13], v41 offset0:10 offset1:11
	ds_read2_b32 v[14:15], v41 offset0:12 offset1:13
	ds_read2_b32 v[32:33], v41 offset0:14 offset1:15
	v_cvt_pk_bf16_f32 v2, v2, v3
	v_cvt_pk_bf16_f32 v3, v4, v5
	v_mul_f32_e32 v1, 0x4f7ffffe, v1
	v_cvt_u32_f32_e32 v1, v1
	v_cvt_pk_bf16_f32 v4, v6, v7
	v_cvt_pk_bf16_f32 v5, v8, v9
	v_readfirstlane_b32 s25, v1
	s_mul_i32 s20, s20, s25
	s_mul_hi_u32 s20, s25, s20
	s_add_i32 s25, s25, s20
	s_mul_hi_u32 s20, s19, s25
	s_mul_i32 s25, s20, s13
	s_sub_i32 s19, s19, s25
	s_add_i32 s25, s20, 1
	s_sub_i32 s26, s19, s13
	s_cmp_ge_u32 s19, s13
	s_cselect_b32 s20, s25, s20
	s_cselect_b32 s19, s26, s19
	s_add_i32 s25, s20, 1
	s_cmp_ge_u32 s19, s13
	s_cselect_b32 s13, s25, s20
	s_xor_b32 s13, s13, s16
	s_sub_i32 s13, s13, s16
	s_mul_i32 s12, s13, s12
	v_lshl_add_u32 v1, s13, 6, v129
	s_sub_i32 s16, s17, s12
	v_mad_i64_i32 v[36:37], s[12:13], v1, s18, 0
	s_lshl_b32 s12, s16, 7
	v_lshl_add_u64 v[36:37], v[36:37], 1, s[14:15]
	s_ashr_i32 s13, s12, 31
	v_lshl_add_u64 v[36:37], s[12:13], 1, v[36:37]
	v_mov_b32_e32 v1, v35
	v_lshl_add_u64 v[36:37], v[36:37], 0, v[0:1]
	global_store_dwordx4 v[36:37], v[2:5], off
	s_andn2_b64 vcc, exec, s[6:7]
	s_mov_b32 s25, s24
	s_waitcnt lgkmcnt(3)
	v_cvt_pk_bf16_f32 v2, v10, v11
	s_waitcnt lgkmcnt(2)
	v_cvt_pk_bf16_f32 v3, v12, v13
	s_waitcnt lgkmcnt(1)
	v_cvt_pk_bf16_f32 v4, v14, v15
	s_waitcnt lgkmcnt(0)
	v_cvt_pk_bf16_f32 v5, v32, v33
	global_store_dwordx4 v[36:37], v[2:5], off offset:16
	s_mov_b32 s20, s11
	s_waitcnt vmcnt(2)
	v_mov_b32_e32 v6, v18
	v_mov_b32_e32 v33, v20
	v_mov_b32_e32 v1, v21
	v_mov_b32_e32 v2, v22
	v_mov_b32_e32 v3, v23
	v_mov_b32_e32 v4, v16
	v_mov_b32_e32 v5, v17
	v_mov_b32_e32 v7, v19
	v_mov_b32_e32 v8, v28
	v_mov_b32_e32 v9, v29
	v_mov_b32_e32 v10, v30
	v_mov_b32_e32 v11, v31
	v_mov_b32_e32 v12, v24
	v_mov_b32_e32 v13, v25
	v_mov_b32_e32 v14, v26
	v_mov_b32_e32 v15, v27
	s_cbranch_vccz .LBB0_1320

; __device__ __forceinline__ void transpose_jobs(const TJob* jobs, int njobs, int bi, int nblk, LAS unsigned char* lds) {
;     ...
;     f32x4 v[4]; int curj = 0, base = 0;
;     int t = bi;
;     auto locate = [&](int tt, int& jj, int& bb) { while (tt >= bb + (jobs[jj].Nout >> 6) * (jobs[jj].K >> 7)) { bb += (jobs[jj].Nout >> 6) * (jobs[jj].K >> 7); ++jj; } };
;     if (t < total) { locate(t, curj, base); tjob_load(jobs[curj], t - base, v); }
;     while (t < total) {
;         const int tn = t + nblk; int nj = curj, nb = base; f32x4 w[4];
;         if (tn < total) { locate(tn, nj, nb); tjob_load(jobs[nj], tn - nb, w); }
.LBB0_1426:
	s_or_b64 exec, exec, s[6:7]
	s_movk_i32 s20, 0x7f
	s_movk_i32 s21, 0xfff
	s_movk_i32 s22, 0x2410
	v_lshlrev_b32_e32 v0, 1, v42
	s_mov_b32 s24, s2
	s_waitcnt vmcnt(0)
	s_branch .LBB0_1429

; #define LAS __attribute__((address_space(3)))
; __device__ __forceinline__ u32x4 pack8(const float* f) { u32x4 w; w.x = pk2(f[0], f[1]); w.y = pk2(f[2], f[3]); w.z = pk2(f[4], f[5]); w.w = pk2(f[6], f[7]); return w; }
; __device__ __forceinline__ void tjob_store(const TJob& j, int tile, const f32x4 (&v)[4], LAS float* s) {
;     const int tid = threadIdx.x, nkt = j.K >> 7, tn = tile / nkt, tk = tile - tn * nkt;
;     const int nq = tid & 15, kr = tid >> 4;
;     __syncthreads();
; #pragma unroll
;     for (int i = 0; i < 4; ++i)
; #pragma unroll
;         for (int q = 0; q < 4; ++q) s[(4 * nq + q) * 129 + kr + 32 * i] = v[i][q];
;     __syncthreads();
;     const int n = tid >> 3, k16 = (tid & 7) * 16;
;     float f[16];
; #pragma unroll
;     for (int i = 0; i < 16; ++i) f[i] = s[n * 129 + k16 + i];
;     bf16_t* d = j.dst + (size_t)(tn * 64 + n) * j.ld_dst + tk * 128 + k16;
;     *(u32x4*)d = pack8(f); *(u32x4*)(d + 8) = pack8(f + 8);
; }
; __device__ __forceinline__ void transpose_jobs(const TJob* jobs, int njobs, int bi, int nblk, LAS unsigned char* lds) {
;     LAS float* s = (LAS float*)lds;
;     int total = 0;
;     for (int q = 0; q < njobs; ++q) total += (jobs[q].Nout >> 6) * (jobs[q].K >> 7);
;     f32x4 v[4]; int curj = 0, base = 0;
;     int t = bi;
;     auto locate = [&](int tt, int& jj, int& bb) { while (tt >= bb + (jobs[jj].Nout >> 6) * (jobs[jj].K >> 7)) { bb += (jobs[jj].Nout >> 6) * (jobs[jj].K >> 7); ++jj; } };
;     if (t < total) { locate(t, curj, base); tjob_load(jobs[curj], t - base, v); }
;     while (t < total) {
;         const int tn = t + nblk; int nj = curj, nb = base; f32x4 w[4];
;         if (tn < total) { locate(tn, nj, nb); tjob_load(jobs[nj], tn - nb, w); }
;         tjob_store(jobs[curj], t - base, v, s);
;         if (tn < total) {
; #pragma unroll
;             for (int i = 0; i < 4; ++i) v[i] = w[i]; }
;         t = tn; curj = nj; base = nb;
;     }
.LBB0_1428:
	s_mul_i32 s11, s11, 40
	s_mul_hi_u32 s12, s10, 40
	s_add_i32 s12, s12, s11
	s_mul_i32 s10, s10, 40
	s_add_u32 s10, s0, s10
	v_add_u32_e32 v32, v39, v40
	s_addc_u32 s11, s1, s12
	s_barrier
	ds_write2_b32 v32, v33, v4 offset1:32
	ds_write2_b32 v32, v1, v5 offset0:129 offset1:161
	v_add_u32_e32 v1, 0x400, v32
	ds_write2_b32 v1, v2, v6 offset0:2 offset1:34
	ds_write2_b32 v1, v3, v7 offset0:131 offset1:163
	ds_write2_b32 v32, v8, v12 offset0:64 offset1:96
	ds_write2_b32 v32, v9, v13 offset0:193 offset1:225
	ds_write2_b32 v1, v10, v14 offset0:66 offset1:98
	ds_write2_b32 v1, v11, v15 offset0:195 offset1:227
	s_waitcnt lgkmcnt(0)
	s_barrier
	s_load_dword s14, s[10:11], 0x13c
	s_load_dwordx2 s[12:13], s[10:11], 0x130
	s_load_dword s16, s[10:11], 0x144
	s_sub_i32 s15, s24, s19
	s_abs_i32 s17, s15
	ds_read2_b32 v[2:3], v41 offset1:1
	ds_read2_b32 v[4:5], v41 offset0:2 offset1:3
	ds_read2_b32 v[6:7], v41 offset0:4 offset1:5
	ds_read2_b32 v[8:9], v41 offset0:6 offset1:7
	s_waitcnt lgkmcnt(0)
	s_ashr_i32 s10, s14, 7
	s_abs_i32 s11, s10
	v_cvt_f32_u32_e32 v1, s11
	s_sub_i32 s19, 0, s11
	s_xor_b32 s14, s15, s10
	s_ashr_i32 s14, s14, 31
	v_rcp_iflag_f32_e32 v1, v1
	ds_read2_b32 v[10:11], v41 offset0:8 offset1:9
	ds_read2_b32 v[12:13], v41 offset0:10 offset1:11
	ds_read2_b32 v[14:15], v41 offset0:12 offset1:13
	ds_read2_b32 v[32:33], v41 offset0:14 offset1:15
	v_cvt_pk_bf16_f32 v2, v2, v3
	v_cvt_pk_bf16_f32 v3, v4, v5
	v_mul_f32_e32 v1, 0x4f7ffffe, v1
	v_cvt_u32_f32_e32 v1, v1
	v_cvt_pk_bf16_f32 v4, v6, v7
	v_cvt_pk_bf16_f32 v5, v8, v9
	v_readfirstlane_b32 s24, v1
	s_mul_i32 s19, s19, s24
	s_mul_hi_u32 s19, s24, s19
	s_add_i32 s24, s24, s19
	s_mul_hi_u32 s19, s17, s24
	s_mul_i32 s24, s19, s11
	s_sub_i32 s17, s17, s24
	s_add_i32 s24, s19, 1
	s_sub_i32 s25, s17, s11
	s_cmp_ge_u32 s17, s11
	s_cselect_b32 s19, s24, s19
	s_cselect_b32 s17, s25, s17
	s_add_i32 s24, s19, 1
	s_cmp_ge_u32 s17, s11
	s_cselect_b32 s11, s24, s19
	s_xor_b32 s11, s11, s14
	s_sub_i32 s11, s11, s14
	s_mul_i32 s10, s11, s10
	v_lshl_add_u32 v1, s11, 6, v86
	s_sub_i32 s14, s15, s10
	v_mad_i64_i32 v[36:37], s[10:11], v1, s16, 0
	s_lshl_b32 s10, s14, 7
	v_lshl_add_u64 v[36:37], v[36:37], 1, s[12:13]
	s_ashr_i32 s11, s10, 31
	v_lshl_add_u64 v[36:37], s[10:11], 1, v[36:37]
	v_mov_b32_e32 v1, v35
	v_lshl_add_u64 v[36:37], v[36:37], 0, v[0:1]
	global_store_dwordx4 v[36:37], v[2:5], off
	s_andn2_b64 vcc, exec, s[6:7]
	s_mov_b32 s24, s23
	s_waitcnt lgkmcnt(3)
	v_cvt_pk_bf16_f32 v2, v10, v11
	s_waitcnt lgkmcnt(2)
	v_cvt_pk_bf16_f32 v3, v12, v13
	s_waitcnt lgkmcnt(1)
	v_cvt_pk_bf16_f32 v4, v14, v15
	s_waitcnt lgkmcnt(0)
	v_cvt_pk_bf16_f32 v5, v32, v33
	global_store_dwordx4 v[36:37], v[2:5], off offset:16
	s_mov_b32 s19, s9
	s_waitcnt vmcnt(2)
	v_mov_b32_e32 v6, v18
	v_mov_b32_e32 v33, v20
	v_mov_b32_e32 v1, v21
	v_mov_b32_e32 v2, v22
	v_mov_b32_e32 v3, v23
	v_mov_b32_e32 v4, v16
	v_mov_b32_e32 v5, v17
	v_mov_b32_e32 v7, v19
	v_mov_b32_e32 v8, v28
	v_mov_b32_e32 v9, v29
	v_mov_b32_e32 v10, v30
	v_mov_b32_e32 v11, v31
	v_mov_b32_e32 v12, v24
	v_mov_b32_e32 v13, v25
	v_mov_b32_e32 v14, v26
	v_mov_b32_e32 v15, v27
	s_cbranch_vccz .LBB0_1463

; __device__ __forceinline__ void transpose_jobs(const TJob* jobs, int njobs, int bi, int nblk, LAS unsigned char* lds) {
;     ...
;     f32x4 v[4]; int curj = 0, base = 0;
;     int t = bi;
;     auto locate = [&](int tt, int& jj, int& bb) { while (tt >= bb + (jobs[jj].Nout >> 6) * (jobs[jj].K >> 7)) { bb += (jobs[jj].Nout >> 6) * (jobs[jj].K >> 7); ++jj; } };
;     if (t < total) { locate(t, curj, base); tjob_load(jobs[curj], t - base, v); }
;     while (t < total) {
;         const int tn = t + nblk; int nj = curj, nb = base; f32x4 w[4];
;         if (tn < total) { locate(tn, nj, nb); tjob_load(jobs[nj], tn - nb, w); }
.LBB0_1499:
	s_or_b64 exec, exec, s[6:7]
	s_add_i32 s24, s96, 0xffffff78
	s_movk_i32 s25, 0x7f
	s_movk_i32 s26, 0xfff
	s_movk_i32 s27, 0x2410
	v_lshlrev_b32_e32 v0, 1, v150
	s_waitcnt vmcnt(0)
	s_branch .LBB0_1502

; #define LAS __attribute__((address_space(3)))
; __device__ __forceinline__ u32x4 pack8(const float* f) { u32x4 w; w.x = pk2(f[0], f[1]); w.y = pk2(f[2], f[3]); w.z = pk2(f[4], f[5]); w.w = pk2(f[6], f[7]); return w; }
; __device__ __forceinline__ void tjob_store(const TJob& j, int tile, const f32x4 (&v)[4], LAS float* s) {
;     const int tid = threadIdx.x, nkt = j.K >> 7, tn = tile / nkt, tk = tile - tn * nkt;
;     const int nq = tid & 15, kr = tid >> 4;
;     __syncthreads();
; #pragma unroll
;     for (int i = 0; i < 4; ++i)
; #pragma unroll
;         for (int q = 0; q < 4; ++q) s[(4 * nq + q) * 129 + kr + 32 * i] = v[i][q];
;     __syncthreads();
;     const int n = tid >> 3, k16 = (tid & 7) * 16;
;     float f[16];
; #pragma unroll
;     for (int i = 0; i < 16; ++i) f[i] = s[n * 129 + k16 + i];
;     bf16_t* d = j.dst + (size_t)(tn * 64 + n) * j.ld_dst + tk * 128 + k16;
;     *(u32x4*)d = pack8(f); *(u32x4*)(d + 8) = pack8(f + 8);
; }
; __device__ __forceinline__ void transpose_jobs(const TJob* jobs, int njobs, int bi, int nblk, LAS unsigned char* lds) {
;     LAS float* s = (LAS float*)lds;
;     int total = 0;
;     for (int q = 0; q < njobs; ++q) total += (jobs[q].Nout >> 6) * (jobs[q].K >> 7);
;     f32x4 v[4]; int curj = 0, base = 0;
;     int t = bi;
;     auto locate = [&](int tt, int& jj, int& bb) { while (tt >= bb + (jobs[jj].Nout >> 6) * (jobs[jj].K >> 7)) { bb += (jobs[jj].Nout >> 6) * (jobs[jj].K >> 7); ++jj; } };
;     if (t < total) { locate(t, curj, base); tjob_load(jobs[curj], t - base, v); }
;     while (t < total) {
;         const int tn = t + nblk; int nj = curj, nb = base; f32x4 w[4];
;         if (tn < total) { locate(tn, nj, nb); tjob_load(jobs[nj], tn - nb, w); }
;         tjob_store(jobs[curj], t - base, v, s);
;         if (tn < total) {
; #pragma unroll
;             for (int i = 0; i < 4; ++i) v[i] = w[i]; }
;         t = tn; curj = nj; base = nb;
;     }
.LBB0_1501:
	s_mul_i32 s15, s15, 40
	s_mul_hi_u32 s16, s14, 40
	s_add_i32 s16, s16, s15
	s_mul_i32 s14, s14, 40
	s_add_u32 s14, s0, s14
	v_add_u32_e32 v32, v39, v40
	s_addc_u32 s15, s1, s16
	s_barrier
	ds_write2_b32 v32, v33, v4 offset1:32
	ds_write2_b32 v32, v1, v5 offset0:129 offset1:161
	v_add_u32_e32 v1, 0x400, v32
	ds_write2_b32 v1, v2, v6 offset0:2 offset1:34
	ds_write2_b32 v1, v3, v7 offset0:131 offset1:163
	ds_write2_b32 v32, v8, v12 offset0:64 offset1:96
	ds_write2_b32 v32, v9, v13 offset0:193 offset1:225
	ds_write2_b32 v1, v10, v14 offset0:66 offset1:98
	ds_write2_b32 v1, v11, v15 offset0:195 offset1:227
	s_waitcnt lgkmcnt(0)
	s_barrier
	s_load_dword s18, s[14:15], 0x164
	s_load_dwordx2 s[16:17], s[14:15], 0x158
	s_load_dword s20, s[14:15], 0x16c
	s_sub_i32 s19, s22, s23
	s_abs_i32 s21, s19
	ds_read2_b32 v[2:3], v41 offset1:1
	ds_read2_b32 v[4:5], v41 offset0:2 offset1:3
	ds_read2_b32 v[6:7], v41 offset0:4 offset1:5
	ds_read2_b32 v[8:9], v41 offset0:6 offset1:7
	s_waitcnt lgkmcnt(0)
	s_ashr_i32 s14, s18, 7
	s_abs_i32 s15, s14
	v_cvt_f32_u32_e32 v1, s15
	s_sub_i32 s22, 0, s15
	s_xor_b32 s18, s19, s14
	s_ashr_i32 s18, s18, 31
	v_rcp_iflag_f32_e32 v1, v1
	ds_read2_b32 v[10:11], v41 offset0:8 offset1:9
	ds_read2_b32 v[12:13], v41 offset0:10 offset1:11
	ds_read2_b32 v[14:15], v41 offset0:12 offset1:13
	ds_read2_b32 v[32:33], v41 offset0:14 offset1:15
	v_cvt_pk_bf16_f32 v2, v2, v3
	v_cvt_pk_bf16_f32 v3, v4, v5
	v_mul_f32_e32 v1, 0x4f7ffffe, v1
	v_cvt_u32_f32_e32 v1, v1
	v_cvt_pk_bf16_f32 v4, v6, v7
	v_cvt_pk_bf16_f32 v5, v8, v9
	v_readfirstlane_b32 s23, v1
	s_mul_i32 s22, s22, s23
	s_mul_hi_u32 s22, s23, s22
	s_add_i32 s23, s23, s22
	s_mul_hi_u32 s22, s21, s23
	s_mul_i32 s23, s22, s15
	s_sub_i32 s21, s21, s23
	s_add_i32 s23, s22, 1
	s_sub_i32 s29, s21, s15
	s_cmp_ge_u32 s21, s15
	s_cselect_b32 s22, s23, s22
	s_cselect_b32 s21, s29, s21
	s_add_i32 s23, s22, 1
	s_cmp_ge_u32 s21, s15
	s_cselect_b32 s15, s23, s22
	s_xor_b32 s15, s15, s18
	s_sub_i32 s15, s15, s18
	s_mul_i32 s14, s15, s14
	v_lshl_add_u32 v1, s15, 6, v129
	s_sub_i32 s18, s19, s14
	v_mad_i64_i32 v[36:37], s[14:15], v1, s20, 0
	s_lshl_b32 s14, s18, 7
	v_lshl_add_u64 v[36:37], v[36:37], 1, s[16:17]
	s_ashr_i32 s15, s14, 31
	v_lshl_add_u64 v[36:37], s[14:15], 1, v[36:37]
	v_mov_b32_e32 v1, v35
	v_lshl_add_u64 v[36:37], v[36:37], 0, v[0:1]
	global_store_dwordx4 v[36:37], v[2:5], off
	s_andn2_b64 vcc, exec, s[6:7]
	s_mov_b32 s22, s28
	s_waitcnt lgkmcnt(3)
	v_cvt_pk_bf16_f32 v2, v10, v11
	s_waitcnt lgkmcnt(2)
	v_cvt_pk_bf16_f32 v3, v12, v13
	s_waitcnt lgkmcnt(1)
	v_cvt_pk_bf16_f32 v4, v14, v15
	s_waitcnt lgkmcnt(0)
	v_cvt_pk_bf16_f32 v5, v32, v33
	global_store_dwordx4 v[36:37], v[2:5], off offset:16
	s_mov_b32 s23, s13
	s_waitcnt vmcnt(2)
	v_mov_b32_e32 v6, v18
	v_mov_b32_e32 v33, v20
	v_mov_b32_e32 v1, v21
	v_mov_b32_e32 v2, v22
	v_mov_b32_e32 v3, v23
	v_mov_b32_e32 v4, v16
	v_mov_b32_e32 v5, v17
	v_mov_b32_e32 v7, v19
	v_mov_b32_e32 v8, v28
	v_mov_b32_e32 v9, v29
	v_mov_b32_e32 v10, v30
	v_mov_b32_e32 v11, v31
	v_mov_b32_e32 v12, v24
	v_mov_b32_e32 v13, v25
	v_mov_b32_e32 v14, v26
	v_mov_b32_e32 v15, v27
	s_cbranch_vccz .LBB0_1536

; __device__ __forceinline__ void transpose_jobs(const TJob* jobs, int njobs, int bi, int nblk, LAS unsigned char* lds) {
;     ...
;     f32x4 v[4]; int curj = 0, base = 0;
;     int t = bi;
;     auto locate = [&](int tt, int& jj, int& bb) { while (tt >= bb + (jobs[jj].Nout >> 6) * (jobs[jj].K >> 7)) { bb += (jobs[jj].Nout >> 6) * (jobs[jj].K >> 7); ++jj; } };
;     if (t < total) { locate(t, curj, base); tjob_load(jobs[curj], t - base, v); }
;     while (t < total) {
;         const int tn = t + nblk; int nj = curj, nb = base; f32x4 w[4];
;         if (tn < total) { locate(tn, nj, nb); tjob_load(jobs[nj], tn - nb, w); }
.LBB0_1552:
	s_or_b64 exec, exec, s[6:7]
	s_sub_i32 s3, s96, s3
	s_movk_i32 s21, 0x7f
	s_movk_i32 s22, 0xfff
	s_movk_i32 s23, 0x2410
	v_lshlrev_b32_e32 v0, 1, v42
	s_waitcnt vmcnt(0)
	s_branch .LBB0_1555

; #define LAS __attribute__((address_space(3)))
; __device__ __forceinline__ u32x4 pack8(const float* f) { u32x4 w; w.x = pk2(f[0], f[1]); w.y = pk2(f[2], f[3]); w.z = pk2(f[4], f[5]); w.w = pk2(f[6], f[7]); return w; }
; __device__ __forceinline__ void tjob_store(const TJob& j, int tile, const f32x4 (&v)[4], LAS float* s) {
;     const int tid = threadIdx.x, nkt = j.K >> 7, tn = tile / nkt, tk = tile - tn * nkt;
;     const int nq = tid & 15, kr = tid >> 4;
;     __syncthreads();
; #pragma unroll
;     for (int i = 0; i < 4; ++i)
; #pragma unroll
;         for (int q = 0; q < 4; ++q) s[(4 * nq + q) * 129 + kr + 32 * i] = v[i][q];
;     __syncthreads();
;     const int n = tid >> 3, k16 = (tid & 7) * 16;
;     float f[16];
; #pragma unroll
;     for (int i = 0; i < 16; ++i) f[i] = s[n * 129 + k16 + i];
;     bf16_t* d = j.dst + (size_t)(tn * 64 + n) * j.ld_dst + tk * 128 + k16;
;     *(u32x4*)d = pack8(f); *(u32x4*)(d + 8) = pack8(f + 8);
; }
; __device__ __forceinline__ void transpose_jobs(const TJob* jobs, int njobs, int bi, int nblk, LAS unsigned char* lds) {
;     LAS float* s = (LAS float*)lds;
;     int total = 0;
;     for (int q = 0; q < njobs; ++q) total += (jobs[q].Nout >> 6) * (jobs[q].K >> 7);
;     f32x4 v[4]; int curj = 0, base = 0;
;     int t = bi;
;     auto locate = [&](int tt, int& jj, int& bb) { while (tt >= bb + (jobs[jj].Nout >> 6) * (jobs[jj].K >> 7)) { bb += (jobs[jj].Nout >> 6) * (jobs[jj].K >> 7); ++jj; } };
;     if (t < total) { locate(t, curj, base); tjob_load(jobs[curj], t - base, v); }
;     while (t < total) {
;         const int tn = t + nblk; int nj = curj, nb = base; f32x4 w[4];
;         if (tn < total) { locate(tn, nj, nb); tjob_load(jobs[nj], tn - nb, w); }
;         tjob_store(jobs[curj], t - base, v, s);
;         if (tn < total) {
; #pragma unroll
;             for (int i = 0; i < 4; ++i) v[i] = w[i]; }
;         t = tn; curj = nj; base = nb;
;     }
.LBB0_1554:
	s_mul_i32 s11, s11, 40
	s_mul_hi_u32 s12, s10, 40
	s_add_i32 s12, s12, s11
	s_mul_i32 s10, s10, 40
	s_add_u32 s10, s0, s10
	v_add_u32_e32 v32, v39, v40
	s_addc_u32 s11, s1, s12
	s_barrier
	ds_write2_b32 v32, v33, v4 offset1:32
	ds_write2_b32 v32, v1, v5 offset0:129 offset1:161
	v_add_u32_e32 v1, 0x400, v32
	ds_write2_b32 v1, v2, v6 offset0:2 offset1:34
	ds_write2_b32 v1, v3, v7 offset0:131 offset1:163
	ds_write2_b32 v32, v8, v12 offset0:64 offset1:96
	ds_write2_b32 v32, v9, v13 offset0:193 offset1:225
	ds_write2_b32 v1, v10, v14 offset0:66 offset1:98
	ds_write2_b32 v1, v11, v15 offset0:195 offset1:227
	s_waitcnt lgkmcnt(0)
	s_barrier
	s_load_dword s14, s[10:11], 0x13c
	s_load_dwordx2 s[12:13], s[10:11], 0x130
	s_load_dword s16, s[10:11], 0x144
	s_sub_i32 s15, s19, s20
	s_abs_i32 s17, s15
	ds_read2_b32 v[2:3], v41 offset1:1
	ds_read2_b32 v[4:5], v41 offset0:2 offset1:3
	ds_read2_b32 v[6:7], v41 offset0:4 offset1:5
	ds_read2_b32 v[8:9], v41 offset0:6 offset1:7
	s_waitcnt lgkmcnt(0)
	s_ashr_i32 s10, s14, 7
	s_abs_i32 s11, s10
	v_cvt_f32_u32_e32 v1, s11
	s_sub_i32 s19, 0, s11
	s_xor_b32 s14, s15, s10
	s_ashr_i32 s14, s14, 31
	v_rcp_iflag_f32_e32 v1, v1
	ds_read2_b32 v[10:11], v41 offset0:8 offset1:9
	ds_read2_b32 v[12:13], v41 offset0:10 offset1:11
	ds_read2_b32 v[14:15], v41 offset0:12 offset1:13
	ds_read2_b32 v[32:33], v41 offset0:14 offset1:15
	v_cvt_pk_bf16_f32 v2, v2, v3
	v_cvt_pk_bf16_f32 v3, v4, v5
	v_mul_f32_e32 v1, 0x4f7ffffe, v1
	v_cvt_u32_f32_e32 v1, v1
	v_cvt_pk_bf16_f32 v4, v6, v7
	v_cvt_pk_bf16_f32 v5, v8, v9
	v_readfirstlane_b32 s20, v1
	s_mul_i32 s19, s19, s20
	s_mul_hi_u32 s19, s20, s19
	s_add_i32 s20, s20, s19
	s_mul_hi_u32 s19, s17, s20
	s_mul_i32 s20, s19, s11
	s_sub_i32 s17, s17, s20
	s_add_i32 s20, s19, 1
	s_sub_i32 s25, s17, s11
	s_cmp_ge_u32 s17, s11
	s_cselect_b32 s19, s20, s19
	s_cselect_b32 s17, s25, s17
	s_add_i32 s20, s19, 1
	s_cmp_ge_u32 s17, s11
	s_cselect_b32 s11, s20, s19
	s_xor_b32 s11, s11, s14
	s_sub_i32 s11, s11, s14
	s_mul_i32 s10, s11, s10
	v_lshl_add_u32 v1, s11, 6, v86
	s_sub_i32 s14, s15, s10
	v_mad_i64_i32 v[36:37], s[10:11], v1, s16, 0
	s_lshl_b32 s10, s14, 7
	v_lshl_add_u64 v[36:37], v[36:37], 1, s[12:13]
	s_ashr_i32 s11, s10, 31
	v_lshl_add_u64 v[36:37], s[10:11], 1, v[36:37]
	v_mov_b32_e32 v1, v35
	v_lshl_add_u64 v[36:37], v[36:37], 0, v[0:1]
	global_store_dwordx4 v[36:37], v[2:5], off
	s_andn2_b64 vcc, exec, s[6:7]
	s_mov_b32 s19, s24
	s_waitcnt lgkmcnt(3)
	v_cvt_pk_bf16_f32 v2, v10, v11
	s_waitcnt lgkmcnt(2)
	v_cvt_pk_bf16_f32 v3, v12, v13
	s_waitcnt lgkmcnt(1)
	v_cvt_pk_bf16_f32 v4, v14, v15
	s_waitcnt lgkmcnt(0)
	v_cvt_pk_bf16_f32 v5, v32, v33
	global_store_dwordx4 v[36:37], v[2:5], off offset:16
	s_mov_b32 s20, s9
	s_waitcnt vmcnt(2)
	v_mov_b32_e32 v6, v18
	v_mov_b32_e32 v33, v20
	v_mov_b32_e32 v1, v21
	v_mov_b32_e32 v2, v22
	v_mov_b32_e32 v3, v23
	v_mov_b32_e32 v4, v16
	v_mov_b32_e32 v5, v17
	v_mov_b32_e32 v7, v19
	v_mov_b32_e32 v8, v28
	v_mov_b32_e32 v9, v29
	v_mov_b32_e32 v10, v30
	v_mov_b32_e32 v11, v31
	v_mov_b32_e32 v12, v24
	v_mov_b32_e32 v13, v25
	v_mov_b32_e32 v14, v26
	v_mov_b32_e32 v15, v27
	s_cbranch_vccz .LBB0_1589
